# K-loops: duplicate back-to-back lgkmcnt(0) waits removed on top of static priority
# speedup vs baseline: 1.0168x; 1.0010x over previous
; #define PG8_STAGE(bufoff, gbase, voff) do { _Pragma("unroll") for (int _i = 0; _i < 2; ++_i) \
;     __builtin_amdgcn_global_load_lds((const unsigned*)((const char*)(gbase) + (voff)[_i]), (LAS unsigned*)(lds + (bufoff) + ldsw + _i * 8192), 16, 0, 0); } while (0)
; #define PG8_LDA(dst, b, h) do { _Pragma("unroll") for (int m = 0; m < 4; ++m) _Pragma("unroll") for (int k = 0; k < 2; ++k) dst[m][k] = *(const LAS bf16x8*)(lds + PG8_SA(b, h) + aoff + m * 2048 + k * 1024); } while (0)
; #define PG8_LDB(dst, b, h) do { _Pragma("unroll") for (int n = 0; n < 2; ++n) _Pragma("unroll") for (int k = 0; k < 2; ++k) dst[n][k] = *(const LAS bf16x8*)(lds + PG8_SB(b, h) + boff + n * 2048 + k * 1024); } while (0)
; #define PG8_WAIT_L(n) asm volatile("s_waitcnt lgkmcnt(" #n ")" ::: "memory")
; #define PG8_BAR __builtin_amdgcn_s_barrier()
; #define PG8_SCHED __builtin_amdgcn_sched_barrier(0)
; template <class Epi>
; DI void gemm_phase(int wv, LAS unsigned char* lds, const Gemm g, const StaticOrder& S, const Epi& E) {
;     ...
;     for (int t = 0; t < nt; t += 2) {
;       const bool last = (t == nt - 2);
;       const char* a1 = cA + (size_t)(t + 1) * kstep;
;       const char* a2 = last ? nA : cA + (size_t)(t + 2) * kstep; const char* b2 = last ? nB : cB + (size_t)(t + 2) * kstep;
;       const char* a3 = a2 + kstep; const char* b3 = b2 + kstep;
;       PG8_LDB(B0, 0, 0); PG8_SCHED; PG8_LDA(At, 0, 0); PG8_STAGE(PG8_SA(1, 1), a1 + hstep, voffA);
;       PG8_WAIT_L(8); PG8_BAR; PG8_WAIT_L(0); PG8_MMA(0, 0, At, B0); PG8_BAR; PG8_SCHED;
;       PG8_LDB(B1, 0, 1); PG8_STAGE(PG8_SB(0, 0), b2, voffA);
;       PG8_BAR; PG8_WAIT_L(0); PG8_MMA(0, 1, At, B1); PG8_BAR;
;       PG8_LDA(At, 0, 1); PG8_STAGE(PG8_SA(0, 0), a2, voffA);
;       PG8_BAR; PG8_WAIT_L(0); PG8_MMA(1, 0, At, B0); PG8_BAR; PG8_SCHED;
.Lgprio_a:
.LBB0_209:
	s_add_u32 s22, s20, 0xfffc0080
	s_addc_u32 s23, s21, -1
	s_add_i32 s63, 0, 0x10000
	v_add_u32_e32 v142, s63, v193
	ds_read_b128 v[130:133], v142
	ds_read_b128 v[134:137], v142 offset:1024
	ds_read_b128 v[138:141], v142 offset:2048
	ds_read_b128 v[142:145], v142 offset:3072
	s_cmp_eq_u32 s62, 12
	s_cselect_b32 s25, s15, s23
	s_cselect_b32 s24, s54, s22
	s_cselect_b32 s23, s13, s61
	s_cselect_b32 s22, s57, s60
	v_lshl_add_u64 v[206:207], s[20:21], 0, v[166:167]
	s_add_i32 m0, s29, 0xc000
	ds_read_b128 v[146:149], v205
	ds_read_b128 v[150:153], v205 offset:1024
	ds_read_b128 v[154:157], v205 offset:2048
	ds_read_b128 v[158:161], v205 offset:3072
	ds_read_b128 v[170:173], v205 offset:4096
	ds_read_b128 v[174:177], v205 offset:5120
	ds_read_b128 v[178:181], v205 offset:6144
	ds_read_b128 v[182:185], v205 offset:7168
	global_load_lds_dwordx4 v[206:207], off
	v_lshl_add_u64 v[206:207], s[20:21], 0, v[168:169]
	s_add_i32 m0, s29, 0xe000
	s_nop 0
	global_load_lds_dwordx4 v[206:207], off
	s_waitcnt lgkmcnt(8)
	s_barrier
	s_waitcnt lgkmcnt(0)
	v_mfma_f32_16x16x32_f16 v[126:129], v[130:133], v[146:149], v[126:129]
	v_mfma_f32_16x16x32_f16 v[122:125], v[138:141], v[146:149], v[122:125]
	v_mfma_f32_16x16x32_f16 v[118:121], v[130:133], v[154:157], v[118:121]
	v_mfma_f32_16x16x32_f16 v[114:117], v[138:141], v[154:157], v[114:117]
	v_mfma_f32_16x16x32_f16 v[110:113], v[130:133], v[170:173], v[110:113]
	v_mfma_f32_16x16x32_f16 v[106:109], v[138:141], v[170:173], v[106:109]
	v_mfma_f32_16x16x32_f16 v[102:105], v[130:133], v[178:181], v[102:105]
	v_mfma_f32_16x16x32_f16 v[98:101], v[138:141], v[178:181], v[98:101]
	v_mfma_f32_16x16x32_f16 v[126:129], v[134:137], v[150:153], v[126:129]
	v_mfma_f32_16x16x32_f16 v[122:125], v[142:145], v[150:153], v[122:125]
	v_mfma_f32_16x16x32_f16 v[118:121], v[134:137], v[158:161], v[118:121]
	v_mfma_f32_16x16x32_f16 v[114:117], v[142:145], v[158:161], v[114:117]
	v_mfma_f32_16x16x32_f16 v[110:113], v[134:137], v[174:177], v[110:113]
	v_mfma_f32_16x16x32_f16 v[106:109], v[142:145], v[174:177], v[106:109]
	v_mfma_f32_16x16x32_f16 v[102:105], v[134:137], v[182:185], v[102:105]
	v_mfma_f32_16x16x32_f16 v[98:101], v[142:145], v[182:185], v[98:101]
	s_barrier
	s_add_i32 s70, 0, 0x14000
	s_add_i32 s63, s63, s27
	v_add_u32_e32 v186, s70, v193
	v_lshl_add_u64 v[222:223], s[22:23], 0, v[162:163]
	s_mov_b32 m0, s63
	ds_read_b128 v[206:209], v186
	ds_read_b128 v[210:213], v186 offset:1024
	ds_read_b128 v[214:217], v186 offset:2048
	ds_read_b128 v[218:221], v186 offset:3072
	global_load_lds_dwordx4 v[222:223], off
	v_lshl_add_u64 v[224:225], s[22:23], 0, v[164:165]
	s_add_i32 m0, s63, 0x2000
	s_nop 0
	global_load_lds_dwordx4 v[224:225], off
	s_barrier
	s_waitcnt lgkmcnt(0)
	v_mfma_f32_16x16x32_f16 v[94:97], v[206:209], v[146:149], v[94:97]
	v_mfma_f32_16x16x32_f16 v[90:93], v[214:217], v[146:149], v[90:93]
	v_mfma_f32_16x16x32_f16 v[86:89], v[206:209], v[154:157], v[86:89]
	v_mfma_f32_16x16x32_f16 v[82:85], v[214:217], v[154:157], v[82:85]
	v_mfma_f32_16x16x32_f16 v[78:81], v[206:209], v[170:173], v[78:81]
	v_mfma_f32_16x16x32_f16 v[74:77], v[214:217], v[170:173], v[74:77]
	v_mfma_f32_16x16x32_f16 v[70:73], v[206:209], v[178:181], v[70:73]
	v_mfma_f32_16x16x32_f16 v[66:69], v[214:217], v[178:181], v[66:69]
	v_mfma_f32_16x16x32_f16 v[94:97], v[210:213], v[150:153], v[94:97]
	v_mfma_f32_16x16x32_f16 v[90:93], v[218:221], v[150:153], v[90:93]
	v_mfma_f32_16x16x32_f16 v[86:89], v[210:213], v[158:161], v[86:89]
	v_mfma_f32_16x16x32_f16 v[82:85], v[218:221], v[158:161], v[82:85]
	v_mfma_f32_16x16x32_f16 v[78:81], v[210:213], v[174:177], v[78:81]
	v_mfma_f32_16x16x32_f16 v[74:77], v[218:221], v[174:177], v[74:77]
	v_mfma_f32_16x16x32_f16 v[70:73], v[210:213], v[182:185], v[70:73]
	v_mfma_f32_16x16x32_f16 v[66:69], v[218:221], v[182:185], v[66:69]
	s_mov_b32 m0, s29
	v_lshl_add_u64 v[226:227], s[24:25], 0, v[162:163]
	s_barrier
	ds_read_b128 v[146:149], v205 offset:16384
	ds_read_b128 v[150:153], v205 offset:17408
	ds_read_b128 v[154:157], v205 offset:18432
	ds_read_b128 v[158:161], v205 offset:19456
	ds_read_b128 v[170:173], v205 offset:20480
	ds_read_b128 v[174:177], v205 offset:21504
	ds_read_b128 v[178:181], v205 offset:22528
	ds_read_b128 v[182:185], v205 offset:23552
	global_load_lds_dwordx4 v[226:227], off
	v_lshl_add_u64 v[230:231], s[24:25], 0, v[164:165]
	s_mov_b32 m0, s34
	s_nop 0
	global_load_lds_dwordx4 v[230:231], off
	s_barrier
	s_waitcnt lgkmcnt(0)
	v_mfma_f32_16x16x32_f16 v[62:65], v[130:133], v[146:149], v[62:65]
	v_mfma_f32_16x16x32_f16 v[58:61], v[138:141], v[146:149], v[58:61]
	v_mfma_f32_16x16x32_f16 v[54:57], v[130:133], v[154:157], v[54:57]
	v_mfma_f32_16x16x32_f16 v[50:53], v[138:141], v[154:157], v[50:53]
	v_mfma_f32_16x16x32_f16 v[46:49], v[130:133], v[170:173], v[46:49]
	v_mfma_f32_16x16x32_f16 v[42:45], v[138:141], v[170:173], v[42:45]
	v_mfma_f32_16x16x32_f16 v[38:41], v[130:133], v[178:181], v[38:41]
	v_mfma_f32_16x16x32_f16 v[34:37], v[138:141], v[178:181], v[34:37]
	v_mfma_f32_16x16x32_f16 v[62:65], v[134:137], v[150:153], v[62:65]
	v_mfma_f32_16x16x32_f16 v[58:61], v[142:145], v[150:153], v[58:61]
	v_mfma_f32_16x16x32_f16 v[54:57], v[134:137], v[158:161], v[54:57]
	v_mfma_f32_16x16x32_f16 v[50:53], v[142:145], v[158:161], v[50:53]
	v_mfma_f32_16x16x32_f16 v[46:49], v[134:137], v[174:177], v[46:49]
	v_mfma_f32_16x16x32_f16 v[42:45], v[142:145], v[174:177], v[42:45]
	v_mfma_f32_16x16x32_f16 v[38:41], v[134:137], v[182:185], v[38:41]
	v_mfma_f32_16x16x32_f16 v[34:37], v[142:145], v[182:185], v[34:37]
	s_barrier
; #define PG8_STAGE(bufoff, gbase, voff) do { _Pragma("unroll") for (int _i = 0; _i < 2; ++_i) \
;     __builtin_amdgcn_global_load_lds((const unsigned*)((const char*)(gbase) + (voff)[_i]), (LAS unsigned*)(lds + (bufoff) + ldsw + _i * 8192), 16, 0, 0); } while (0)
; #define PG8_LDA(dst, b, h) do { _Pragma("unroll") for (int m = 0; m < 4; ++m) _Pragma("unroll") for (int k = 0; k < 2; ++k) dst[m][k] = *(const LAS bf16x8*)(lds + PG8_SA(b, h) + aoff + m * 2048 + k * 1024); } while (0)
; #define PG8_LDB(dst, b, h) do { _Pragma("unroll") for (int n = 0; n < 2; ++n) _Pragma("unroll") for (int k = 0; k < 2; ++k) dst[n][k] = *(const LAS bf16x8*)(lds + PG8_SB(b, h) + boff + n * 2048 + k * 1024); } while (0)
; #define PG8_WAIT_V(n) asm volatile("s_waitcnt vmcnt(" #n ")" ::: "memory")
; #define PG8_WAIT_L(n) asm volatile("s_waitcnt lgkmcnt(" #n ")" ::: "memory")
; #define PG8_BAR __builtin_amdgcn_s_barrier()
; #define PG8_SCHED __builtin_amdgcn_sched_barrier(0)
; template <class Epi>
; DI void gemm_phase(int wv, LAS unsigned char* lds, const Gemm g, const StaticOrder& S, const Epi& E) {
;     ...
;       PG8_STAGE(PG8_SB(0, 1), b2 + hstep, voffA);
;       PG8_WAIT_V(6); PG8_BAR; PG8_MMA(1, 1, At, B1); PG8_BAR;
;       PG8_LDB(B0, 1, 0); PG8_SCHED; PG8_LDA(At, 1, 0); PG8_STAGE(PG8_SA(0, 1), a2 + hstep, voffA);
;       PG8_WAIT_L(8); PG8_BAR; PG8_WAIT_L(0); PG8_MMA(0, 0, At, B0); PG8_BAR; PG8_SCHED;
;       PG8_LDB(B1, 1, 1); PG8_STAGE(PG8_SB(1, 0), b3, voffA);
;       PG8_BAR; PG8_WAIT_L(0); PG8_MMA(0, 1, At, B1); PG8_BAR;
;       PG8_LDA(At, 1, 1); PG8_STAGE(PG8_SA(1, 0), a3, voffA);
;       PG8_BAR; PG8_WAIT_L(0); PG8_MMA(1, 0, At, B0); PG8_BAR; PG8_SCHED;
	s_add_u32 s64, s22, 0x40000
	s_addc_u32 s65, s23, 0
	s_add_i32 s63, s70, s27
	v_lshl_add_u64 v[130:131], s[64:65], 0, v[162:163]
	s_mov_b32 m0, s63
	s_nop 0
	global_load_lds_dwordx4 v[130:131], off
	v_lshl_add_u64 v[130:131], s[64:65], 0, v[164:165]
	s_add_i32 m0, s63, 0x2000
	s_nop 0
	global_load_lds_dwordx4 v[130:131], off
	s_waitcnt vmcnt(6)
	s_barrier
	v_mfma_f32_16x16x32_f16 v[28:31], v[206:209], v[146:149], v[28:31]
	v_mfma_f32_16x16x32_f16 v[24:27], v[214:217], v[146:149], v[24:27]
	v_mfma_f32_16x16x32_f16 v[20:23], v[206:209], v[154:157], v[20:23]
	v_mfma_f32_16x16x32_f16 v[16:19], v[214:217], v[154:157], v[16:19]
	v_mfma_f32_16x16x32_f16 v[12:15], v[206:209], v[170:173], v[12:15]
	v_mfma_f32_16x16x32_f16 v[8:11], v[214:217], v[170:173], v[8:11]
	v_mfma_f32_16x16x32_f16 v[4:7], v[206:209], v[178:181], v[4:7]
	v_mfma_f32_16x16x32_f16 v[0:3], v[214:217], v[178:181], v[0:3]
	v_mfma_f32_16x16x32_f16 v[28:31], v[210:213], v[150:153], v[28:31]
	v_mfma_f32_16x16x32_f16 v[24:27], v[218:221], v[150:153], v[24:27]
	v_mfma_f32_16x16x32_f16 v[20:23], v[210:213], v[158:161], v[20:23]
	v_mfma_f32_16x16x32_f16 v[16:19], v[218:221], v[158:161], v[16:19]
	v_mfma_f32_16x16x32_f16 v[12:15], v[210:213], v[174:177], v[12:15]
	v_mfma_f32_16x16x32_f16 v[8:11], v[218:221], v[174:177], v[8:11]
	v_mfma_f32_16x16x32_f16 v[4:7], v[210:213], v[182:185], v[4:7]
	v_mfma_f32_16x16x32_f16 v[0:3], v[218:221], v[182:185], v[0:3]
	s_add_i32 s63, 0, 0x18000
	v_add_u32_e32 v142, s63, v193
	s_barrier
	ds_read_b128 v[130:133], v142
	ds_read_b128 v[134:137], v142 offset:1024
	ds_read_b128 v[138:141], v142 offset:2048
	ds_read_b128 v[142:145], v142 offset:3072
	s_add_u32 s24, s24, 0x40000
	s_addc_u32 s25, s25, 0
	s_mov_b32 m0, s35
	v_lshl_add_u64 v[206:207], s[24:25], 0, v[162:163]
	ds_read_b128 v[146:149], v205 offset:32768
	ds_read_b128 v[150:153], v205 offset:33792
	ds_read_b128 v[154:157], v205 offset:34816
	ds_read_b128 v[158:161], v205 offset:35840
	ds_read_b128 v[170:173], v205 offset:36864
	ds_read_b128 v[174:177], v205 offset:37888
	ds_read_b128 v[178:181], v205 offset:38912
	ds_read_b128 v[182:185], v205 offset:39936
	global_load_lds_dwordx4 v[206:207], off
	v_lshl_add_u64 v[206:207], s[24:25], 0, v[164:165]
	s_mov_b32 m0, s36
	s_nop 0
	global_load_lds_dwordx4 v[206:207], off
	s_waitcnt lgkmcnt(8)
	s_barrier
	s_waitcnt lgkmcnt(0)
	v_mfma_f32_16x16x32_f16 v[126:129], v[130:133], v[146:149], v[126:129]
	v_mfma_f32_16x16x32_f16 v[122:125], v[138:141], v[146:149], v[122:125]
	v_mfma_f32_16x16x32_f16 v[118:121], v[130:133], v[154:157], v[118:121]
	v_mfma_f32_16x16x32_f16 v[114:117], v[138:141], v[154:157], v[114:117]
	v_mfma_f32_16x16x32_f16 v[110:113], v[130:133], v[170:173], v[110:113]
	v_mfma_f32_16x16x32_f16 v[106:109], v[138:141], v[170:173], v[106:109]
	v_mfma_f32_16x16x32_f16 v[102:105], v[130:133], v[178:181], v[102:105]
	v_mfma_f32_16x16x32_f16 v[98:101], v[138:141], v[178:181], v[98:101]
	v_mfma_f32_16x16x32_f16 v[126:129], v[134:137], v[150:153], v[126:129]
	v_mfma_f32_16x16x32_f16 v[122:125], v[142:145], v[150:153], v[122:125]
	v_mfma_f32_16x16x32_f16 v[118:121], v[134:137], v[158:161], v[118:121]
	v_mfma_f32_16x16x32_f16 v[114:117], v[142:145], v[158:161], v[114:117]
	v_mfma_f32_16x16x32_f16 v[110:113], v[134:137], v[174:177], v[110:113]
	v_mfma_f32_16x16x32_f16 v[106:109], v[142:145], v[174:177], v[106:109]
	v_mfma_f32_16x16x32_f16 v[102:105], v[134:137], v[182:185], v[102:105]
	v_mfma_f32_16x16x32_f16 v[98:101], v[142:145], v[182:185], v[98:101]
	s_barrier
	s_add_i32 s24, 0, 0x1c000
	s_add_i32 s25, s63, s27
	v_add_u32_e32 v186, s24, v193
	v_lshl_add_u64 v[222:223], v[222:223], 0, s[2:3]
	s_mov_b32 m0, s25
	ds_read_b128 v[206:209], v186
	ds_read_b128 v[210:213], v186 offset:1024
	ds_read_b128 v[214:217], v186 offset:2048
	ds_read_b128 v[218:221], v186 offset:3072
	global_load_lds_dwordx4 v[222:223], off
	v_lshl_add_u64 v[222:223], v[224:225], 0, s[2:3]
	s_add_i32 m0, s25, 0x2000
	s_nop 0
	global_load_lds_dwordx4 v[222:223], off
	s_barrier
	s_waitcnt lgkmcnt(0)
	v_mfma_f32_16x16x32_f16 v[94:97], v[206:209], v[146:149], v[94:97]
	v_mfma_f32_16x16x32_f16 v[90:93], v[214:217], v[146:149], v[90:93]
	v_mfma_f32_16x16x32_f16 v[86:89], v[206:209], v[154:157], v[86:89]
	v_mfma_f32_16x16x32_f16 v[82:85], v[214:217], v[154:157], v[82:85]
	v_mfma_f32_16x16x32_f16 v[78:81], v[206:209], v[170:173], v[78:81]
	v_mfma_f32_16x16x32_f16 v[74:77], v[214:217], v[170:173], v[74:77]
	v_mfma_f32_16x16x32_f16 v[70:73], v[206:209], v[178:181], v[70:73]
	v_mfma_f32_16x16x32_f16 v[66:69], v[214:217], v[178:181], v[66:69]
	v_mfma_f32_16x16x32_f16 v[94:97], v[210:213], v[150:153], v[94:97]
	v_mfma_f32_16x16x32_f16 v[90:93], v[218:221], v[150:153], v[90:93]
	v_mfma_f32_16x16x32_f16 v[86:89], v[210:213], v[158:161], v[86:89]
	v_mfma_f32_16x16x32_f16 v[82:85], v[218:221], v[158:161], v[82:85]
	v_mfma_f32_16x16x32_f16 v[78:81], v[210:213], v[174:177], v[78:81]
	v_mfma_f32_16x16x32_f16 v[74:77], v[218:221], v[174:177], v[74:77]
	v_mfma_f32_16x16x32_f16 v[70:73], v[210:213], v[182:185], v[70:73]
	v_mfma_f32_16x16x32_f16 v[66:69], v[218:221], v[182:185], v[66:69]
	s_mov_b32 m0, s37
	v_lshl_add_u64 v[222:223], v[226:227], 0, s[2:3]
	s_barrier
; #define LAS __attribute__((address_space(3)))
; #define PG8_STAGE(bufoff, gbase, voff) do { _Pragma("unroll") for (int _i = 0; _i < 2; ++_i) \
;     __builtin_amdgcn_global_load_lds((const unsigned*)((const char*)(gbase) + (voff)[_i]), (LAS unsigned*)(lds + (bufoff) + ldsw + _i * 8192), 16, 0, 0); } while (0)
; #define PG8_WAIT_V(n) asm volatile("s_waitcnt vmcnt(" #n ")" ::: "memory")
; #define PG8_WAIT_L(n) asm volatile("s_waitcnt lgkmcnt(" #n ")" ::: "memory")
; #define PG8_BAR __builtin_amdgcn_s_barrier()
; #define PG8_SCHED __builtin_amdgcn_sched_barrier(0)
; template <class Epi>
; DI void gemm_phase(int wv, LAS unsigned char* lds, const Gemm g, const StaticOrder& S, const Epi& E) {
;     ...
;       PG8_BAR; PG8_WAIT_L(0); PG8_MMA(1, 0, At, B0); PG8_BAR; PG8_SCHED;
;       PG8_STAGE(PG8_SB(1, 1), b3 + hstep, voffA);
;       PG8_WAIT_V(6); PG8_BAR; PG8_MMA(1, 1, At, B1); PG8_BAR;
;   DI void operator()(const f32x4 (&acc)[2][2][4][2], const pg8::Unit& u, int wr, int wc, int fr, int fq, LAS unsigned char* lds, int ui, int wid) const {
;     const int colg = u.pn * 256 + wc * 32 + 8 * fq, hcol = u.pn * 128 + wc * 32 + 8 * fq;
;     f32x4 c1g[2], c2g[2], c1u[2], c2u[2];
;     int fq_ = fq, fr_ = fr; asm volatile("" : "+v"(fq_), "+v"(fr_));
;     const LAS float* cl = (const LAS float*)(lds + 139264 + (ui & 1) * 2048) + wc * 32 + 8 * fq_;
; #pragma unroll
;     for (int n = 0; n < 2; ++n) { c1g[n] = *(const LAS f32x4*)(cl + 4 * n); c2g[n] = *(const LAS f32x4*)(cl + 256 + 4 * n); c1u[n] = *(const LAS f32x4*)(cl + 128 + 4 * n); c2u[n] = *(const LAS f32x4*)(cl + 256 + 128 + 4 * n); }
;     float ra[8], rb[8];
;     const LAS float* sl = (const LAS float*)(lds + 131072 + wid * 1024);
; #pragma unroll
;     for (int i = 0; i < 8; ++i) { typedef float f32x2_ __attribute__((ext_vector_type(2))); const f32x2_ sv = *(const LAS f32x2_*)(sl + (i >> 2) * 128 + ((i & 3) * 16 + fr_) * 2);
;       const float mu = sv.x * (1.0f / 1024.0f), var = fmaxf(sv.y * (1.0f / 1024.0f) - mu * mu, 0.f), rstd = rsqrtf(var + 1e-5f); ra[i] = rstd; rb[i] = -rstd * mu; }
; #pragma unroll
;     for (int ai = 0; ai < 2; ++ai)
; #pragma unroll
;       for (int m = 0; m < 4; ++m) {
;         const int row = u.pm * 256 + ai * 128 + wr * 64 + m * 16 + fr; const float a = ra[ai * 4 + m], bb = rb[ai * 4 + m];
	ds_read_b128 v[146:149], v205 offset:49152
	ds_read_b128 v[150:153], v205 offset:50176
	ds_read_b128 v[154:157], v205 offset:51200
	ds_read_b128 v[158:161], v205 offset:52224
	ds_read_b128 v[170:173], v205 offset:53248
	ds_read_b128 v[174:177], v205 offset:54272
	ds_read_b128 v[178:181], v205 offset:55296
	ds_read_b128 v[182:185], v205 offset:56320
	global_load_lds_dwordx4 v[222:223], off
	v_lshl_add_u64 v[222:223], v[230:231], 0, s[2:3]
	s_mov_b32 m0, s38
	s_nop 0
	global_load_lds_dwordx4 v[222:223], off
	s_barrier
	s_waitcnt lgkmcnt(0)
	v_mfma_f32_16x16x32_f16 v[62:65], v[130:133], v[146:149], v[62:65]
	v_mfma_f32_16x16x32_f16 v[58:61], v[138:141], v[146:149], v[58:61]
	v_mfma_f32_16x16x32_f16 v[54:57], v[130:133], v[154:157], v[54:57]
	v_mfma_f32_16x16x32_f16 v[50:53], v[138:141], v[154:157], v[50:53]
	v_mfma_f32_16x16x32_f16 v[46:49], v[130:133], v[170:173], v[46:49]
	v_mfma_f32_16x16x32_f16 v[42:45], v[138:141], v[170:173], v[42:45]
	v_mfma_f32_16x16x32_f16 v[38:41], v[130:133], v[178:181], v[38:41]
	v_mfma_f32_16x16x32_f16 v[34:37], v[138:141], v[178:181], v[34:37]
	v_mfma_f32_16x16x32_f16 v[62:65], v[134:137], v[150:153], v[62:65]
	v_mfma_f32_16x16x32_f16 v[58:61], v[142:145], v[150:153], v[58:61]
	v_mfma_f32_16x16x32_f16 v[54:57], v[134:137], v[158:161], v[54:57]
	v_mfma_f32_16x16x32_f16 v[50:53], v[142:145], v[158:161], v[50:53]
	v_mfma_f32_16x16x32_f16 v[46:49], v[134:137], v[174:177], v[46:49]
	v_mfma_f32_16x16x32_f16 v[42:45], v[142:145], v[174:177], v[42:45]
	v_mfma_f32_16x16x32_f16 v[38:41], v[134:137], v[182:185], v[38:41]
	v_mfma_f32_16x16x32_f16 v[34:37], v[142:145], v[182:185], v[34:37]
	s_barrier
	s_add_u32 s22, s22, 0x40080
	s_addc_u32 s23, s23, 0
	s_add_i32 s24, s24, s27
	v_lshl_add_u64 v[130:131], s[22:23], 0, v[162:163]
	s_mov_b32 m0, s24
	s_nop 0
	global_load_lds_dwordx4 v[130:131], off
	v_lshl_add_u64 v[130:131], s[22:23], 0, v[164:165]
	s_add_i32 m0, s24, 0x2000
	s_nop 0
	global_load_lds_dwordx4 v[130:131], off
	s_waitcnt vmcnt(6)
	s_barrier
	v_mfma_f32_16x16x32_f16 v[28:31], v[206:209], v[146:149], v[28:31]
	v_mfma_f32_16x16x32_f16 v[24:27], v[214:217], v[146:149], v[24:27]
	v_mfma_f32_16x16x32_f16 v[20:23], v[206:209], v[154:157], v[20:23]
	v_mfma_f32_16x16x32_f16 v[16:19], v[214:217], v[154:157], v[16:19]
	v_mfma_f32_16x16x32_f16 v[12:15], v[206:209], v[170:173], v[12:15]
	v_mfma_f32_16x16x32_f16 v[8:11], v[214:217], v[170:173], v[8:11]
	v_mfma_f32_16x16x32_f16 v[4:7], v[206:209], v[178:181], v[4:7]
	v_mfma_f32_16x16x32_f16 v[0:3], v[214:217], v[178:181], v[0:3]
	v_mfma_f32_16x16x32_f16 v[28:31], v[210:213], v[150:153], v[28:31]
	v_mfma_f32_16x16x32_f16 v[24:27], v[218:221], v[150:153], v[24:27]
	v_mfma_f32_16x16x32_f16 v[20:23], v[210:213], v[158:161], v[20:23]
	v_mfma_f32_16x16x32_f16 v[16:19], v[218:221], v[158:161], v[16:19]
	v_mfma_f32_16x16x32_f16 v[12:15], v[210:213], v[174:177], v[12:15]
	v_mfma_f32_16x16x32_f16 v[8:11], v[218:221], v[174:177], v[8:11]
	v_mfma_f32_16x16x32_f16 v[4:7], v[210:213], v[182:185], v[4:7]
	v_mfma_f32_16x16x32_f16 v[0:3], v[218:221], v[182:185], v[0:3]
	s_add_i32 s62, s62, 2
	s_add_u32 s20, s20, 0x100
	s_addc_u32 s21, s21, 0
	s_add_u32 s60, s60, 0x100
	s_addc_u32 s61, s61, 0
	s_cmp_gt_u32 s62, 13
	s_barrier
	s_cbranch_scc0 .LBB0_209
	v_readlane_b32 s20, v253, 8
	v_readlane_b32 s21, v253, 9
	s_andn2_b64 vcc, exec, s[20:21]
	s_mov_b32 s22, 0x800000
	s_cbranch_vccnz .LBB0_213
	v_lshl_or_b32 v130, s49, 7, v203
	v_lshl_add_u32 v134, s50, 8, v191
	v_ashrrev_i32_e32 v131, 31, v130
	v_mov_b64_e32 v[132:133], s[10:11]
	v_or_b32_e32 v136, 16, v134
	v_or_b32_e32 v137, 32, v134
	v_or_b32_e32 v138, 48, v134
	v_add_u32_e32 v139, 0x80, v134
	v_add_u32_e32 v140, 0x90, v134
	v_add_u32_e32 v141, 0xa0, v134
	v_add_u32_e32 v142, 0xb0, v134
	v_mad_i64_i32 v[134:135], s[20:21], v134, s91, v[132:133]
	v_lshlrev_b64 v[130:131], 1, v[130:131]
	v_lshl_add_u64 v[170:171], v[134:135], 0, v[130:131]
	v_mad_i64_i32 v[134:135], s[20:21], v136, s91, v[132:133]
	v_lshl_add_u64 v[172:173], v[134:135], 0, v[130:131]
	v_mad_i64_i32 v[134:135], s[20:21], v137, s91, v[132:133]
	v_lshl_add_u64 v[174:175], v[134:135], 0, v[130:131]
	v_mad_i64_i32 v[134:135], s[20:21], v138, s91, v[132:133]
	v_lshl_add_u64 v[176:177], v[134:135], 0, v[130:131]
	v_mad_i64_i32 v[134:135], s[20:21], v139, s91, v[132:133]
	s_lshl_b32 s13, s51, 11
	v_lshl_add_u64 v[178:179], v[134:135], 0, v[130:131]
	v_mad_i64_i32 v[134:135], s[20:21], v140, s91, v[132:133]
	v_readlane_b32 s44, v252, 2
	s_and_b32 s13, s13, 0x800
	v_lshl_add_u64 v[180:181], v[134:135], 0, v[130:131]
	v_mad_i64_i32 v[134:135], s[20:21], v141, s91, v[132:133]
	v_mad_i64_i32 v[132:133], s[20:21], v142, s91, v[132:133]
	v_readlane_b32 s50, v252, 8
	s_add_i32 s13, s40, s13
	v_lshl_add_u64 v[182:183], v[134:135], 0, v[130:131]
	v_lshl_add_u64 v[184:185], v[132:133], 0, v[130:131]
	s_mov_b32 s20, 0x3a800000
	s_mov_b32 s15, s50
	v_readlane_b32 s45, v252, 3
	v_readlane_b32 s46, v252, 4
	v_readlane_b32 s47, v252, 5
	v_readlane_b32 s48, v252, 6
	v_readlane_b32 s49, v252, 7
	v_readlane_b32 s51, v252, 9

; #define PG8_STAGE(bufoff, gbase, voff) do { _Pragma("unroll") for (int _i = 0; _i < 2; ++_i) \
;     __builtin_amdgcn_global_load_lds((const unsigned*)((const char*)(gbase) + (voff)[_i]), (LAS unsigned*)(lds + (bufoff) + ldsw + _i * 8192), 16, 0, 0); } while (0)
; #define PG8_LDA(dst, b, h) do { _Pragma("unroll") for (int m = 0; m < 4; ++m) _Pragma("unroll") for (int k = 0; k < 2; ++k) dst[m][k] = *(const LAS bf16x8*)(lds + PG8_SA(b, h) + aoff + m * 2048 + k * 1024); } while (0)
; #define PG8_LDB(dst, b, h) do { _Pragma("unroll") for (int n = 0; n < 2; ++n) _Pragma("unroll") for (int k = 0; k < 2; ++k) dst[n][k] = *(const LAS bf16x8*)(lds + PG8_SB(b, h) + boff + n * 2048 + k * 1024); } while (0)
; #define PG8_WAIT_V(n) asm volatile("s_waitcnt vmcnt(" #n ")" ::: "memory")
; #define PG8_WAIT_L(n) asm volatile("s_waitcnt lgkmcnt(" #n ")" ::: "memory")
; #define PG8_BAR __builtin_amdgcn_s_barrier()
; #define PG8_SCHED __builtin_amdgcn_sched_barrier(0)
; template <class Epi>
; DI void gemm_phase(int wv, LAS unsigned char* lds, const Gemm g, const StaticOrder& S, const Epi& E) {
;     ...
;       PG8_LDB(B0, 0, 0); PG8_SCHED; PG8_LDA(At, 0, 0); PG8_STAGE(PG8_SA(1, 1), a1 + hstep, voffA);
;       PG8_WAIT_L(8); PG8_BAR; PG8_WAIT_L(0); PG8_MMA(0, 0, At, B0); PG8_BAR; PG8_SCHED;
;       PG8_LDB(B1, 0, 1); PG8_STAGE(PG8_SB(0, 0), b2, voffA);
;       PG8_BAR; PG8_WAIT_L(0); PG8_MMA(0, 1, At, B1); PG8_BAR;
;       PG8_LDA(At, 0, 1); PG8_STAGE(PG8_SA(0, 0), a2, voffA);
;       PG8_BAR; PG8_WAIT_L(0); PG8_MMA(1, 0, At, B0); PG8_BAR; PG8_SCHED;
;       PG8_STAGE(PG8_SB(0, 1), b2 + hstep, voffA);
;       PG8_WAIT_V(6); PG8_BAR; PG8_MMA(1, 1, At, B1); PG8_BAR;
.Lgprio_b:
.LBB0_293:
	s_add_u32 s34, s30, 0xfffc0080
	s_addc_u32 s35, s31, -1
	s_add_i32 s54, 0, 0x10000
	v_add_u32_e32 v150, s54, v181
	ds_read_b128 v[138:141], v150
	ds_read_b128 v[142:145], v150 offset:1024
	ds_read_b128 v[146:149], v150 offset:2048
	ds_read_b128 v[150:153], v150 offset:3072
	s_cmp_eq_u32 s51, 12
	s_cselect_b32 s37, s21, s35
	s_cselect_b32 s36, s29, s34
	s_cselect_b32 s35, s19, s50
	s_cselect_b32 s34, s33, s49
	v_lshl_add_u64 v[178:179], s[30:31], 0, v[134:135]
	s_add_i32 m0, s64, 0xc000
	ds_read_b128 v[154:157], v190
	ds_read_b128 v[158:161], v190 offset:1024
	ds_read_b128 v[162:165], v190 offset:2048
	ds_read_b128 v[166:169], v190 offset:3072
	ds_read_b128 v[170:173], v190 offset:4096
	ds_read_b128 v[202:205], v190 offset:5120
	ds_read_b128 v[206:209], v190 offset:6144
	ds_read_b128 v[210:213], v190 offset:7168
	global_load_lds_dwordx4 v[178:179], off
	v_lshl_add_u64 v[178:179], s[30:31], 0, v[136:137]
	s_add_i32 m0, s64, 0xe000
	s_nop 0
	global_load_lds_dwordx4 v[178:179], off
	s_waitcnt lgkmcnt(8)
	s_barrier
	s_waitcnt lgkmcnt(0)
	v_mfma_f32_16x16x32_f16 v[126:129], v[138:141], v[154:157], v[126:129]
	v_mfma_f32_16x16x32_f16 v[122:125], v[146:149], v[154:157], v[122:125]
	v_mfma_f32_16x16x32_f16 v[110:113], v[138:141], v[162:165], v[110:113]
	v_mfma_f32_16x16x32_f16 v[106:109], v[146:149], v[162:165], v[106:109]
	v_mfma_f32_16x16x32_f16 v[94:97], v[138:141], v[170:173], v[94:97]
	v_mfma_f32_16x16x32_f16 v[90:93], v[146:149], v[170:173], v[90:93]
	v_mfma_f32_16x16x32_f16 v[78:81], v[138:141], v[206:209], v[78:81]
	v_mfma_f32_16x16x32_f16 v[74:77], v[146:149], v[206:209], v[74:77]
	v_mfma_f32_16x16x32_f16 v[126:129], v[142:145], v[158:161], v[126:129]
	v_mfma_f32_16x16x32_f16 v[122:125], v[150:153], v[158:161], v[122:125]
	v_mfma_f32_16x16x32_f16 v[110:113], v[142:145], v[166:169], v[110:113]
	v_mfma_f32_16x16x32_f16 v[106:109], v[150:153], v[166:169], v[106:109]
	v_mfma_f32_16x16x32_f16 v[94:97], v[142:145], v[202:205], v[94:97]
	v_mfma_f32_16x16x32_f16 v[90:93], v[150:153], v[202:205], v[90:93]
	v_mfma_f32_16x16x32_f16 v[78:81], v[142:145], v[210:213], v[78:81]
	v_mfma_f32_16x16x32_f16 v[74:77], v[150:153], v[210:213], v[74:77]
	s_barrier
	s_add_i32 s57, 0, 0x14000
	s_add_i32 s54, s54, s62
	v_add_u32_e32 v174, s57, v181
	v_lshl_add_u64 v[178:179], s[34:35], 0, v[130:131]
	s_mov_b32 m0, s54
	ds_read_b128 v[214:217], v174
	ds_read_b128 v[218:221], v174 offset:1024
	ds_read_b128 v[222:225], v174 offset:2048
	ds_read_b128 v[244:247], v174 offset:3072
	global_load_lds_dwordx4 v[178:179], off
	v_lshl_add_u64 v[192:193], s[34:35], 0, v[132:133]
	s_add_i32 m0, s54, 0x2000
	s_nop 0
	global_load_lds_dwordx4 v[192:193], off
	s_barrier
	s_waitcnt lgkmcnt(0)
	v_mfma_f32_16x16x32_f16 v[118:121], v[214:217], v[154:157], v[118:121]
	v_mfma_f32_16x16x32_f16 v[114:117], v[222:225], v[154:157], v[114:117]
	v_mfma_f32_16x16x32_f16 v[102:105], v[214:217], v[162:165], v[102:105]
	v_mfma_f32_16x16x32_f16 v[98:101], v[222:225], v[162:165], v[98:101]
	v_mfma_f32_16x16x32_f16 v[86:89], v[214:217], v[170:173], v[86:89]
	v_mfma_f32_16x16x32_f16 v[82:85], v[222:225], v[170:173], v[82:85]
	v_mfma_f32_16x16x32_f16 v[70:73], v[214:217], v[206:209], v[70:73]
	v_mfma_f32_16x16x32_f16 v[66:69], v[222:225], v[206:209], v[66:69]
	v_mfma_f32_16x16x32_f16 v[118:121], v[218:221], v[158:161], v[118:121]
	v_mfma_f32_16x16x32_f16 v[114:117], v[244:247], v[158:161], v[114:117]
	v_mfma_f32_16x16x32_f16 v[102:105], v[218:221], v[166:169], v[102:105]
	v_mfma_f32_16x16x32_f16 v[98:101], v[244:247], v[166:169], v[98:101]
	v_mfma_f32_16x16x32_f16 v[86:89], v[218:221], v[202:205], v[86:89]
	v_mfma_f32_16x16x32_f16 v[82:85], v[244:247], v[202:205], v[82:85]
	v_mfma_f32_16x16x32_f16 v[70:73], v[218:221], v[210:213], v[70:73]
	v_mfma_f32_16x16x32_f16 v[66:69], v[244:247], v[210:213], v[66:69]
	s_mov_b32 m0, s64
	v_lshl_add_u64 v[226:227], s[36:37], 0, v[130:131]
	s_barrier
	ds_read_b128 v[154:157], v190 offset:16384
	ds_read_b128 v[158:161], v190 offset:17408
	ds_read_b128 v[162:165], v190 offset:18432
	ds_read_b128 v[166:169], v190 offset:19456
	ds_read_b128 v[170:173], v190 offset:20480
	ds_read_b128 v[202:205], v190 offset:21504
	ds_read_b128 v[206:209], v190 offset:22528
	ds_read_b128 v[210:213], v190 offset:23552
	global_load_lds_dwordx4 v[226:227], off
	v_lshl_add_u64 v[230:231], s[36:37], 0, v[132:133]
	s_mov_b32 m0, s84
	s_nop 0
	global_load_lds_dwordx4 v[230:231], off
	s_barrier
	s_waitcnt lgkmcnt(0)
	v_mfma_f32_16x16x32_f16 v[62:65], v[138:141], v[154:157], v[62:65]
	v_mfma_f32_16x16x32_f16 v[58:61], v[146:149], v[154:157], v[58:61]
	v_mfma_f32_16x16x32_f16 v[46:49], v[138:141], v[162:165], v[46:49]
	v_mfma_f32_16x16x32_f16 v[42:45], v[146:149], v[162:165], v[42:45]
	v_mfma_f32_16x16x32_f16 v[28:31], v[138:141], v[170:173], v[28:31]
	v_mfma_f32_16x16x32_f16 v[24:27], v[146:149], v[170:173], v[24:27]
	v_mfma_f32_16x16x32_f16 v[12:15], v[138:141], v[206:209], v[12:15]
	v_mfma_f32_16x16x32_f16 v[8:11], v[146:149], v[206:209], v[8:11]
	v_mfma_f32_16x16x32_f16 v[62:65], v[142:145], v[158:161], v[62:65]
	v_mfma_f32_16x16x32_f16 v[58:61], v[150:153], v[158:161], v[58:61]
	v_mfma_f32_16x16x32_f16 v[46:49], v[142:145], v[166:169], v[46:49]
	v_mfma_f32_16x16x32_f16 v[42:45], v[150:153], v[166:169], v[42:45]
	v_mfma_f32_16x16x32_f16 v[28:31], v[142:145], v[202:205], v[28:31]
	v_mfma_f32_16x16x32_f16 v[24:27], v[150:153], v[202:205], v[24:27]
	v_mfma_f32_16x16x32_f16 v[12:15], v[142:145], v[210:213], v[12:15]
	v_mfma_f32_16x16x32_f16 v[8:11], v[150:153], v[210:213], v[8:11]
	s_barrier
; #define PG8_STAGE(bufoff, gbase, voff) do { _Pragma("unroll") for (int _i = 0; _i < 2; ++_i) \
;     __builtin_amdgcn_global_load_lds((const unsigned*)((const char*)(gbase) + (voff)[_i]), (LAS unsigned*)(lds + (bufoff) + ldsw + _i * 8192), 16, 0, 0); } while (0)
; #define PG8_LDA(dst, b, h) do { _Pragma("unroll") for (int m = 0; m < 4; ++m) _Pragma("unroll") for (int k = 0; k < 2; ++k) dst[m][k] = *(const LAS bf16x8*)(lds + PG8_SA(b, h) + aoff + m * 2048 + k * 1024); } while (0)
; #define PG8_LDB(dst, b, h) do { _Pragma("unroll") for (int n = 0; n < 2; ++n) _Pragma("unroll") for (int k = 0; k < 2; ++k) dst[n][k] = *(const LAS bf16x8*)(lds + PG8_SB(b, h) + boff + n * 2048 + k * 1024); } while (0)
; #define PG8_WAIT_V(n) asm volatile("s_waitcnt vmcnt(" #n ")" ::: "memory")
; #define PG8_WAIT_L(n) asm volatile("s_waitcnt lgkmcnt(" #n ")" ::: "memory")
; #define PG8_BAR __builtin_amdgcn_s_barrier()
; #define PG8_SCHED __builtin_amdgcn_sched_barrier(0)
; template <class Epi>
; DI void gemm_phase(int wv, LAS unsigned char* lds, const Gemm g, const StaticOrder& S, const Epi& E) {
;     ...
;       PG8_STAGE(PG8_SB(0, 1), b2 + hstep, voffA);
;       PG8_WAIT_V(6); PG8_BAR; PG8_MMA(1, 1, At, B1); PG8_BAR;
;       PG8_LDB(B0, 1, 0); PG8_SCHED; PG8_LDA(At, 1, 0); PG8_STAGE(PG8_SA(0, 1), a2 + hstep, voffA);
;       PG8_WAIT_L(8); PG8_BAR; PG8_WAIT_L(0); PG8_MMA(0, 0, At, B0); PG8_BAR; PG8_SCHED;
;       PG8_LDB(B1, 1, 1); PG8_STAGE(PG8_SB(1, 0), b3, voffA);
;       PG8_BAR; PG8_WAIT_L(0); PG8_MMA(0, 1, At, B1); PG8_BAR;
;       PG8_LDA(At, 1, 1); PG8_STAGE(PG8_SA(1, 0), a3, voffA);
;       PG8_BAR; PG8_WAIT_L(0); PG8_MMA(1, 0, At, B0); PG8_BAR; PG8_SCHED;
	s_add_u32 s70, s34, 0x40000
	s_addc_u32 s71, s35, 0
	s_add_i32 s54, s57, s62
	v_lshl_add_u64 v[138:139], s[70:71], 0, v[130:131]
	s_mov_b32 m0, s54
	s_nop 0
	global_load_lds_dwordx4 v[138:139], off
	v_lshl_add_u64 v[138:139], s[70:71], 0, v[132:133]
	s_add_i32 m0, s54, 0x2000
	s_nop 0
	global_load_lds_dwordx4 v[138:139], off
	s_waitcnt vmcnt(6)
	s_barrier
	v_mfma_f32_16x16x32_f16 v[54:57], v[214:217], v[154:157], v[54:57]
	v_mfma_f32_16x16x32_f16 v[50:53], v[222:225], v[154:157], v[50:53]
	v_mfma_f32_16x16x32_f16 v[38:41], v[214:217], v[162:165], v[38:41]
	v_mfma_f32_16x16x32_f16 v[34:37], v[222:225], v[162:165], v[34:37]
	v_mfma_f32_16x16x32_f16 v[20:23], v[214:217], v[170:173], v[20:23]
	v_mfma_f32_16x16x32_f16 v[16:19], v[222:225], v[170:173], v[16:19]
	v_mfma_f32_16x16x32_f16 v[4:7], v[214:217], v[206:209], v[4:7]
	v_mfma_f32_16x16x32_f16 v[0:3], v[222:225], v[206:209], v[0:3]
	v_mfma_f32_16x16x32_f16 v[54:57], v[218:221], v[158:161], v[54:57]
	v_mfma_f32_16x16x32_f16 v[50:53], v[244:247], v[158:161], v[50:53]
	v_mfma_f32_16x16x32_f16 v[38:41], v[218:221], v[166:169], v[38:41]
	v_mfma_f32_16x16x32_f16 v[34:37], v[244:247], v[166:169], v[34:37]
	v_mfma_f32_16x16x32_f16 v[20:23], v[218:221], v[202:205], v[20:23]
	v_mfma_f32_16x16x32_f16 v[16:19], v[244:247], v[202:205], v[16:19]
	v_mfma_f32_16x16x32_f16 v[4:7], v[218:221], v[210:213], v[4:7]
	v_mfma_f32_16x16x32_f16 v[0:3], v[244:247], v[210:213], v[0:3]
	s_add_i32 s54, 0, 0x18000
	v_add_u32_e32 v150, s54, v181
	s_barrier
	ds_read_b128 v[138:141], v150
	ds_read_b128 v[142:145], v150 offset:1024
	ds_read_b128 v[146:149], v150 offset:2048
	ds_read_b128 v[150:153], v150 offset:3072
	s_add_u32 s36, s36, 0x40000
	s_addc_u32 s37, s37, 0
	s_mov_b32 m0, s90
	v_lshl_add_u64 v[214:215], s[36:37], 0, v[130:131]
	ds_read_b128 v[154:157], v190 offset:32768
	ds_read_b128 v[158:161], v190 offset:33792
	ds_read_b128 v[162:165], v190 offset:34816
	ds_read_b128 v[166:169], v190 offset:35840
	ds_read_b128 v[170:173], v190 offset:36864
	ds_read_b128 v[202:205], v190 offset:37888
	ds_read_b128 v[206:209], v190 offset:38912
	ds_read_b128 v[210:213], v190 offset:39936
	global_load_lds_dwordx4 v[214:215], off
	v_lshl_add_u64 v[214:215], s[36:37], 0, v[132:133]
	s_mov_b32 m0, s91
	s_nop 0
	global_load_lds_dwordx4 v[214:215], off
	s_waitcnt lgkmcnt(8)
	s_barrier
	s_waitcnt lgkmcnt(0)
	v_mfma_f32_16x16x32_f16 v[126:129], v[138:141], v[154:157], v[126:129]
	v_mfma_f32_16x16x32_f16 v[122:125], v[146:149], v[154:157], v[122:125]
	v_mfma_f32_16x16x32_f16 v[110:113], v[138:141], v[162:165], v[110:113]
	v_mfma_f32_16x16x32_f16 v[106:109], v[146:149], v[162:165], v[106:109]
	v_mfma_f32_16x16x32_f16 v[94:97], v[138:141], v[170:173], v[94:97]
	v_mfma_f32_16x16x32_f16 v[90:93], v[146:149], v[170:173], v[90:93]
	v_mfma_f32_16x16x32_f16 v[78:81], v[138:141], v[206:209], v[78:81]
	v_mfma_f32_16x16x32_f16 v[74:77], v[146:149], v[206:209], v[74:77]
	v_mfma_f32_16x16x32_f16 v[126:129], v[142:145], v[158:161], v[126:129]
	v_mfma_f32_16x16x32_f16 v[122:125], v[150:153], v[158:161], v[122:125]
	v_mfma_f32_16x16x32_f16 v[110:113], v[142:145], v[166:169], v[110:113]
	v_mfma_f32_16x16x32_f16 v[106:109], v[150:153], v[166:169], v[106:109]
	v_mfma_f32_16x16x32_f16 v[94:97], v[142:145], v[202:205], v[94:97]
	v_mfma_f32_16x16x32_f16 v[90:93], v[150:153], v[202:205], v[90:93]
	v_mfma_f32_16x16x32_f16 v[78:81], v[142:145], v[210:213], v[78:81]
	v_mfma_f32_16x16x32_f16 v[74:77], v[150:153], v[210:213], v[74:77]
	s_barrier
	s_add_i32 s36, 0, 0x1c000
	s_add_i32 s37, s54, s62
	v_add_u32_e32 v174, s36, v181
	v_lshl_add_u64 v[178:179], v[178:179], 0, s[2:3]
	s_mov_b32 m0, s37
	ds_read_b128 v[214:217], v174
	ds_read_b128 v[218:221], v174 offset:1024
	ds_read_b128 v[222:225], v174 offset:2048
	ds_read_b128 v[244:247], v174 offset:3072
	global_load_lds_dwordx4 v[178:179], off
	v_lshl_add_u64 v[178:179], v[192:193], 0, s[2:3]
	s_add_i32 m0, s37, 0x2000
	s_nop 0
	global_load_lds_dwordx4 v[178:179], off
	s_barrier
	s_waitcnt lgkmcnt(0)
	v_mfma_f32_16x16x32_f16 v[118:121], v[214:217], v[154:157], v[118:121]
	v_mfma_f32_16x16x32_f16 v[114:117], v[222:225], v[154:157], v[114:117]
	v_mfma_f32_16x16x32_f16 v[102:105], v[214:217], v[162:165], v[102:105]
	v_mfma_f32_16x16x32_f16 v[98:101], v[222:225], v[162:165], v[98:101]
	v_mfma_f32_16x16x32_f16 v[86:89], v[214:217], v[170:173], v[86:89]
	v_mfma_f32_16x16x32_f16 v[82:85], v[222:225], v[170:173], v[82:85]
	v_mfma_f32_16x16x32_f16 v[70:73], v[214:217], v[206:209], v[70:73]
	v_mfma_f32_16x16x32_f16 v[66:69], v[222:225], v[206:209], v[66:69]
	v_mfma_f32_16x16x32_f16 v[118:121], v[218:221], v[158:161], v[118:121]
	v_mfma_f32_16x16x32_f16 v[114:117], v[244:247], v[158:161], v[114:117]
	v_mfma_f32_16x16x32_f16 v[102:105], v[218:221], v[166:169], v[102:105]
	v_mfma_f32_16x16x32_f16 v[98:101], v[244:247], v[166:169], v[98:101]
	v_mfma_f32_16x16x32_f16 v[86:89], v[218:221], v[202:205], v[86:89]
	v_mfma_f32_16x16x32_f16 v[82:85], v[244:247], v[202:205], v[82:85]
	v_mfma_f32_16x16x32_f16 v[70:73], v[218:221], v[210:213], v[70:73]
	v_mfma_f32_16x16x32_f16 v[66:69], v[244:247], v[210:213], v[66:69]
	s_mov_b32 m0, s41
	v_lshl_add_u64 v[178:179], v[226:227], 0, s[2:3]
	s_barrier
	ds_read_b128 v[154:157], v190 offset:49152
	ds_read_b128 v[158:161], v190 offset:50176
	ds_read_b128 v[162:165], v190 offset:51200
	ds_read_b128 v[166:169], v190 offset:52224
	ds_read_b128 v[170:173], v190 offset:53248
	ds_read_b128 v[202:205], v190 offset:54272
	ds_read_b128 v[206:209], v190 offset:55296
	ds_read_b128 v[210:213], v190 offset:56320
	global_load_lds_dwordx4 v[178:179], off
	v_lshl_add_u64 v[178:179], v[230:231], 0, s[2:3]
	s_mov_b32 m0, s42
	s_nop 0
	global_load_lds_dwordx4 v[178:179], off
	s_barrier
; #define LAS __attribute__((address_space(3)))
; DI unsigned pk2(float a, float b) { typedef __bf16 bf2 __attribute__((ext_vector_type(2))); bf2 v; v[0] = (__bf16)a; v[1] = (__bf16)b; return __builtin_bit_cast(unsigned, v); }
; #define PG8_STAGE(bufoff, gbase, voff) do { _Pragma("unroll") for (int _i = 0; _i < 2; ++_i) \
;     __builtin_amdgcn_global_load_lds((const unsigned*)((const char*)(gbase) + (voff)[_i]), (LAS unsigned*)(lds + (bufoff) + ldsw + _i * 8192), 16, 0, 0); } while (0)
; #define PG8_WAIT_V(n) asm volatile("s_waitcnt vmcnt(" #n ")" ::: "memory")
; template <class Epi>
; DI void gemm_phase(int wv, LAS unsigned char* lds, const Gemm g, const StaticOrder& S, const Epi& E) {
;     ...
;       PG8_BAR; PG8_WAIT_L(0); PG8_MMA(1, 0, At, B0); PG8_BAR; PG8_SCHED;
;       PG8_STAGE(PG8_SB(1, 1), b3 + hstep, voffA);
;       PG8_WAIT_V(6); PG8_BAR; PG8_MMA(1, 1, At, B1); PG8_BAR;
;   template <int SECT>
;   DI void body(const f32x4 (&acc)[2][2][4][2], const pg8::Unit& u, int wr, int wc, int fr, int fq, LAS unsigned char* lds, int ui, int wid) const {
;     const int col0 = u.pn * 256 + wc * 32 + 8 * fq;
;     int fq_ = fq, fr_ = fr; asm volatile("" : "+v"(fq_), "+v"(fr_));
;     const LAS float* cl = (const LAS float*)(lds + 139264 + (ui & 1) * 3072) + wc * 32 + 8 * fq_;
;     const LAS float* sl = (const LAS float*)(lds + 131072 + wid * 1024);
; #pragma unroll
;     for (int ai = 0; ai < 2; ++ai)
; #pragma unroll
;       for (int m = 0; m < 4; ++m) {
;         const int row = u.pm * 256 + ai * 128 + wr * 64 + m * 16 + fr; float a, bb;
;         { typedef float f32x2_ __attribute__((ext_vector_type(2))); const f32x2_ sv = *(const LAS f32x2_*)(sl + ai * 128 + (m * 16 + fr_) * 2);
;           const float mu = sv.x * (1.0f / 1024.0f), var = fmaxf(sv.y * (1.0f / 1024.0f) - mu * mu, 0.f), rstd = rsqrtf(var + 1e-5f); a = rstd; bb = -rstd * mu; }
; #pragma unroll
;         for (int bj = 0; bj < 2; ++bj) {
;           const int col = col0 + bj * 128;
;           f32x4 v[2];
; #pragma unroll
;           for (int n = 0; n < 2; ++n) v[n] = acc[ai][bj][m][n] * a + (*(const LAS f32x4*)(cl + bj * 128 + 4 * n)) * bb + *(const LAS f32x4*)(cl + 256 + bj * 128 + 4 * n);
;           if (SECT < 0) { u32x4 w; w[0] = pk2(v[0][0], v[0][1]); w[1] = pk2(v[0][2], v[0][3]); w[2] = pk2(v[1][0], v[1][1]); w[3] = pk2(v[1][2], v[1][3]); *(u32x4*)(h + (size_t)row * ld + col) = w; }
	s_waitcnt lgkmcnt(0)
	v_mfma_f32_16x16x32_f16 v[62:65], v[138:141], v[154:157], v[62:65]
	v_mfma_f32_16x16x32_f16 v[58:61], v[146:149], v[154:157], v[58:61]
	v_mfma_f32_16x16x32_f16 v[46:49], v[138:141], v[162:165], v[46:49]
	v_mfma_f32_16x16x32_f16 v[42:45], v[146:149], v[162:165], v[42:45]
	v_mfma_f32_16x16x32_f16 v[28:31], v[138:141], v[170:173], v[28:31]
	v_mfma_f32_16x16x32_f16 v[24:27], v[146:149], v[170:173], v[24:27]
	v_mfma_f32_16x16x32_f16 v[12:15], v[138:141], v[206:209], v[12:15]
	v_mfma_f32_16x16x32_f16 v[8:11], v[146:149], v[206:209], v[8:11]
	v_mfma_f32_16x16x32_f16 v[62:65], v[142:145], v[158:161], v[62:65]
	v_mfma_f32_16x16x32_f16 v[58:61], v[150:153], v[158:161], v[58:61]
	v_mfma_f32_16x16x32_f16 v[46:49], v[142:145], v[166:169], v[46:49]
	v_mfma_f32_16x16x32_f16 v[42:45], v[150:153], v[166:169], v[42:45]
	v_mfma_f32_16x16x32_f16 v[28:31], v[142:145], v[202:205], v[28:31]
	v_mfma_f32_16x16x32_f16 v[24:27], v[150:153], v[202:205], v[24:27]
	v_mfma_f32_16x16x32_f16 v[12:15], v[142:145], v[210:213], v[12:15]
	v_mfma_f32_16x16x32_f16 v[8:11], v[150:153], v[210:213], v[8:11]
	s_barrier
	s_add_u32 s34, s34, 0x40080
	s_addc_u32 s35, s35, 0
	s_add_i32 s36, s36, s62
	v_lshl_add_u64 v[138:139], s[34:35], 0, v[130:131]
	s_mov_b32 m0, s36
	s_nop 0
	global_load_lds_dwordx4 v[138:139], off
	v_lshl_add_u64 v[138:139], s[34:35], 0, v[132:133]
	s_add_i32 m0, s36, 0x2000
	s_nop 0
	global_load_lds_dwordx4 v[138:139], off
	s_waitcnt vmcnt(6)
	s_barrier
	v_mfma_f32_16x16x32_f16 v[54:57], v[214:217], v[154:157], v[54:57]
	v_mfma_f32_16x16x32_f16 v[50:53], v[222:225], v[154:157], v[50:53]
	v_mfma_f32_16x16x32_f16 v[38:41], v[214:217], v[162:165], v[38:41]
	v_mfma_f32_16x16x32_f16 v[34:37], v[222:225], v[162:165], v[34:37]
	v_mfma_f32_16x16x32_f16 v[20:23], v[214:217], v[170:173], v[20:23]
	v_mfma_f32_16x16x32_f16 v[16:19], v[222:225], v[170:173], v[16:19]
	v_mfma_f32_16x16x32_f16 v[4:7], v[214:217], v[206:209], v[4:7]
	v_mfma_f32_16x16x32_f16 v[0:3], v[222:225], v[206:209], v[0:3]
	v_mfma_f32_16x16x32_f16 v[54:57], v[218:221], v[158:161], v[54:57]
	v_mfma_f32_16x16x32_f16 v[50:53], v[244:247], v[158:161], v[50:53]
	v_mfma_f32_16x16x32_f16 v[38:41], v[218:221], v[166:169], v[38:41]
	v_mfma_f32_16x16x32_f16 v[34:37], v[244:247], v[166:169], v[34:37]
	v_mfma_f32_16x16x32_f16 v[20:23], v[218:221], v[202:205], v[20:23]
	v_mfma_f32_16x16x32_f16 v[16:19], v[244:247], v[202:205], v[16:19]
	v_mfma_f32_16x16x32_f16 v[4:7], v[218:221], v[210:213], v[4:7]
	v_mfma_f32_16x16x32_f16 v[0:3], v[244:247], v[210:213], v[0:3]
	s_add_i32 s51, s51, 2
	s_add_u32 s30, s30, 0x100
	s_addc_u32 s31, s31, 0
	s_add_u32 s49, s49, 0x100
	s_addc_u32 s50, s50, 0
	s_cmp_gt_u32 s51, 13
	s_barrier
	s_cbranch_scc0 .LBB0_293
	s_lshl_b32 s21, s26, 8
	s_bitcmp1_b32 s27, 0
	s_cselect_b32 s19, 0xc00, 0
	s_lshl_b32 s27, s28, 8
	v_readlane_b32 s30, v255, 41
	v_add_u32_e32 v170, s27, v180
	v_add_u32_e32 v168, s27, v182
	v_add_u32_e32 v166, s27, v183
	v_add_u32_e32 v162, s27, v184
	v_add_u32_e32 v160, s27, v185
	v_add_u32_e32 v156, s27, v186
	v_add_u32_e32 v152, s27, v187
	v_add_u32_e32 v150, s27, v188
	v_readlane_b32 s31, v255, 42
	s_add_i32 s19, s39, s19
	v_ashrrev_i32_e32 v171, 31, v170
	v_ashrrev_i32_e32 v169, 31, v168
	v_ashrrev_i32_e32 v167, 31, v166
	v_ashrrev_i32_e32 v163, 31, v162
	v_ashrrev_i32_e32 v161, 31, v160
	v_ashrrev_i32_e32 v157, 31, v156
	v_ashrrev_i32_e32 v153, 31, v152
	v_ashrrev_i32_e32 v151, 31, v150
	v_or_b32_e32 v146, s21, v189
	v_mov_b32_e32 v147, v32
	s_mov_b64 s[28:29], -1
	s_and_b64 vcc, exec, s[30:31]
	s_cbranch_vccz .LBB0_296
	v_mov_b32_e32 v140, v177
	v_mov_b32_e32 v141, v175
	s_mov_b32 s27, 0x800000
	v_lshl_add_u32 v141, v141, 3, s65
	ds_read_b64 v[142:143], v141
	v_lshl_add_u32 v140, v140, 5, s19
	v_readlane_b32 s30, v255, 45
	v_ashrrev_i32_e32 v139, 31, v146
	v_mov_b32_e32 v138, v146
	s_waitcnt lgkmcnt(0)
	v_pk_mul_f32 v[142:143], v[142:143], s[44:45] op_sel_hi:[1,0]
	v_lshlrev_b64 v[138:139], 1, v[138:139]
	v_fma_f32 v143, -v142, v142, v143
	v_max_f32_e32 v143, 0, v143
	v_add_f32_e32 v143, 0x3727c5ac, v143
	v_cmp_gt_f32_e32 vcc, s27, v143
	v_mul_f32_e32 v144, 0x4b800000, v143
	s_nop 0
	v_cndmask_b32_e32 v143, v143, v144, vcc
	v_rsq_f32_e32 v143, v143
	s_nop 0
	v_mul_f32_e32 v144, 0x45800000, v143
	v_cndmask_b32_e32 v148, v143, v144, vcc
	v_mul_f32_e64 v154, v142, -v148
	ds_read_b128 v[142:145], v140
	ds_read_b128 v[202:205], v140 offset:16
	s_waitcnt lgkmcnt(0)
	v_pk_mul_f32 v[144:145], v[144:145], v[154:155] op_sel_hi:[1,0]
	v_pk_mul_f32 v[142:143], v[142:143], v[154:155] op_sel_hi:[1,0]
	v_pk_fma_f32 v[164:165], v[128:129], v[148:149], v[144:145] op_sel_hi:[1,0,1]
	v_pk_fma_f32 v[158:159], v[126:127], v[148:149], v[142:143] op_sel_hi:[1,0,1]
	ds_read_b128 v[142:145], v140 offset:1024
	s_waitcnt lgkmcnt(0)
	v_pk_add_f32 v[164:165], v[144:145], v[164:165]
	v_pk_add_f32 v[158:159], v[142:143], v[158:159]
	v_pk_mul_f32 v[142:143], v[204:205], v[154:155] op_sel_hi:[1,0]
	v_pk_mul_f32 v[144:145], v[202:203], v[154:155] op_sel_hi:[1,0]
	v_pk_fma_f32 v[178:179], v[124:125], v[148:149], v[142:143] op_sel_hi:[1,0,1]
	v_pk_fma_f32 v[172:173], v[122:123], v[148:149], v[144:145] op_sel_hi:[1,0,1]
	ds_read_b128 v[142:145], v140 offset:1040
	s_waitcnt lgkmcnt(0)
	v_pk_add_f32 v[178:179], v[144:145], v[178:179]
	v_pk_add_f32 v[144:145], v[142:143], v[172:173]
	v_cvt_pk_bf16_f32 v142, v158, v159
	v_mad_i64_i32 v[158:159], s[28:29], v170, s30, 0
	v_lshl_add_u64 v[158:159], v[158:159], 1, s[10:11]
	v_cvt_pk_bf16_f32 v143, v164, v165
	v_cvt_pk_bf16_f32 v144, v144, v145
	v_cvt_pk_bf16_f32 v145, v178, v179
	v_lshl_add_u64 v[158:159], v[158:159], 0, v[138:139]
	global_store_dwordx4 v[158:159], v[142:145], off
	ds_read_b128 v[142:145], v140 offset:512
	s_waitcnt lgkmcnt(0)
; #define LAS __attribute__((address_space(3)))
; DI unsigned pk2(float a, float b) { typedef __bf16 bf2 __attribute__((ext_vector_type(2))); bf2 v; v[0] = (__bf16)a; v[1] = (__bf16)b; return __builtin_bit_cast(unsigned, v); }
;   template <int SECT>
;   DI void body(const f32x4 (&acc)[2][2][4][2], const pg8::Unit& u, int wr, int wc, int fr, int fq, LAS unsigned char* lds, int ui, int wid) const {
;     ...
;         const int row = u.pm * 256 + ai * 128 + wr * 64 + m * 16 + fr; float a, bb;
;         { typedef float f32x2_ __attribute__((ext_vector_type(2))); const f32x2_ sv = *(const LAS f32x2_*)(sl + ai * 128 + (m * 16 + fr_) * 2);
;           const float mu = sv.x * (1.0f / 1024.0f), var = fmaxf(sv.y * (1.0f / 1024.0f) - mu * mu, 0.f), rstd = rsqrtf(var + 1e-5f); a = rstd; bb = -rstd * mu; }
; #pragma unroll
;         for (int bj = 0; bj < 2; ++bj) {
;           const int col = col0 + bj * 128;
;           f32x4 v[2];
; #pragma unroll
;           for (int n = 0; n < 2; ++n) v[n] = acc[ai][bj][m][n] * a + (*(const LAS f32x4*)(cl + bj * 128 + 4 * n)) * bb + *(const LAS f32x4*)(cl + 256 + bj * 128 + 4 * n);
;           if (SECT < 0) { u32x4 w; w[0] = pk2(v[0][0], v[0][1]); w[1] = pk2(v[0][2], v[0][3]); w[2] = pk2(v[1][0], v[1][1]); w[3] = pk2(v[1][2], v[1][3]); *(u32x4*)(h + (size_t)row * ld + col) = w; }
	v_pk_mul_f32 v[144:145], v[144:145], v[154:155] op_sel_hi:[1,0]
	v_pk_mul_f32 v[142:143], v[142:143], v[154:155] op_sel_hi:[1,0]
	v_pk_fma_f32 v[172:173], v[120:121], v[148:149], v[144:145] op_sel_hi:[1,0,1]
	v_pk_fma_f32 v[164:165], v[118:119], v[148:149], v[142:143] op_sel_hi:[1,0,1]
	ds_read_b128 v[142:145], v140 offset:1536
	s_waitcnt lgkmcnt(0)
	v_pk_add_f32 v[172:173], v[144:145], v[172:173]
	v_pk_add_f32 v[164:165], v[142:143], v[164:165]
	ds_read_b128 v[142:145], v140 offset:528
	s_waitcnt lgkmcnt(0)
	v_pk_mul_f32 v[144:145], v[144:145], v[154:155] op_sel_hi:[1,0]
	v_pk_mul_f32 v[142:143], v[142:143], v[154:155] op_sel_hi:[1,0]
	s_nop 0
	v_pk_fma_f32 v[154:155], v[114:115], v[148:149], v[142:143] op_sel_hi:[1,0,1]
	v_pk_fma_f32 v[148:149], v[116:117], v[148:149], v[144:145] op_sel_hi:[1,0,1]
	ds_read_b128 v[142:145], v140 offset:1552
	s_waitcnt lgkmcnt(0)
	v_pk_add_f32 v[148:149], v[144:145], v[148:149]
	v_pk_add_f32 v[144:145], v[142:143], v[154:155]
	v_cvt_pk_bf16_f32 v142, v164, v165
	v_cvt_pk_bf16_f32 v143, v172, v173
	v_cvt_pk_bf16_f32 v144, v144, v145
	v_cvt_pk_bf16_f32 v145, v148, v149
	global_store_dwordx4 v[158:159], v[142:145], off offset:256
	ds_read_b64 v[142:143], v141 offset:128
	s_waitcnt lgkmcnt(0)
	v_pk_mul_f32 v[142:143], v[142:143], s[44:45] op_sel_hi:[1,0]
	s_nop 0
	v_fma_f32 v143, -v142, v142, v143
	v_max_f32_e32 v143, 0, v143
	v_add_f32_e32 v143, 0x3727c5ac, v143
	v_cmp_gt_f32_e32 vcc, s27, v143
	v_mul_f32_e32 v144, 0x4b800000, v143
	s_nop 0
	v_cndmask_b32_e32 v143, v143, v144, vcc
	v_rsq_f32_e32 v143, v143
	s_nop 0
	v_mul_f32_e32 v144, 0x45800000, v143
	v_cndmask_b32_e32 v148, v143, v144, vcc
	v_mul_f32_e64 v154, v142, -v148
	ds_read_b128 v[142:145], v140
	ds_read_b128 v[202:205], v140 offset:16
	s_waitcnt lgkmcnt(0)
	v_pk_mul_f32 v[144:145], v[144:145], v[154:155] op_sel_hi:[1,0]
	v_pk_mul_f32 v[142:143], v[142:143], v[154:155] op_sel_hi:[1,0]
	v_pk_fma_f32 v[164:165], v[112:113], v[148:149], v[144:145] op_sel_hi:[1,0,1]
	v_pk_fma_f32 v[158:159], v[110:111], v[148:149], v[142:143] op_sel_hi:[1,0,1]
	ds_read_b128 v[142:145], v140 offset:1024
	s_waitcnt lgkmcnt(0)
	v_pk_add_f32 v[164:165], v[144:145], v[164:165]
	v_pk_add_f32 v[158:159], v[142:143], v[158:159]
	v_pk_mul_f32 v[142:143], v[204:205], v[154:155] op_sel_hi:[1,0]
	v_pk_mul_f32 v[144:145], v[202:203], v[154:155] op_sel_hi:[1,0]
	v_pk_fma_f32 v[178:179], v[108:109], v[148:149], v[142:143] op_sel_hi:[1,0,1]
	v_pk_fma_f32 v[172:173], v[106:107], v[148:149], v[144:145] op_sel_hi:[1,0,1]
	ds_read_b128 v[142:145], v140 offset:1040
	s_waitcnt lgkmcnt(0)
	v_pk_add_f32 v[178:179], v[144:145], v[178:179]
	v_pk_add_f32 v[144:145], v[142:143], v[172:173]
	v_cvt_pk_bf16_f32 v142, v158, v159
	v_mad_i64_i32 v[158:159], s[28:29], v168, s30, 0
	v_lshl_add_u64 v[158:159], v[158:159], 1, s[10:11]
	v_cvt_pk_bf16_f32 v143, v164, v165
	v_cvt_pk_bf16_f32 v144, v144, v145
	v_cvt_pk_bf16_f32 v145, v178, v179
	v_lshl_add_u64 v[158:159], v[158:159], 0, v[138:139]
	global_store_dwordx4 v[158:159], v[142:145], off
	ds_read_b128 v[142:145], v140 offset:512
	s_waitcnt lgkmcnt(0)
	v_pk_mul_f32 v[144:145], v[144:145], v[154:155] op_sel_hi:[1,0]
	v_pk_mul_f32 v[142:143], v[142:143], v[154:155] op_sel_hi:[1,0]
	v_pk_fma_f32 v[172:173], v[104:105], v[148:149], v[144:145] op_sel_hi:[1,0,1]
	v_pk_fma_f32 v[164:165], v[102:103], v[148:149], v[142:143] op_sel_hi:[1,0,1]
	ds_read_b128 v[142:145], v140 offset:1536
	s_waitcnt lgkmcnt(0)
	v_pk_add_f32 v[172:173], v[144:145], v[172:173]
	v_pk_add_f32 v[164:165], v[142:143], v[164:165]
	ds_read_b128 v[142:145], v140 offset:528
	s_waitcnt lgkmcnt(0)
	v_pk_mul_f32 v[144:145], v[144:145], v[154:155] op_sel_hi:[1,0]
	v_pk_mul_f32 v[142:143], v[142:143], v[154:155] op_sel_hi:[1,0]
	s_nop 0
	v_pk_fma_f32 v[154:155], v[98:99], v[148:149], v[142:143] op_sel_hi:[1,0,1]
	v_pk_fma_f32 v[148:149], v[100:101], v[148:149], v[144:145] op_sel_hi:[1,0,1]
	ds_read_b128 v[142:145], v140 offset:1552
	s_waitcnt lgkmcnt(0)
	v_pk_add_f32 v[148:149], v[144:145], v[148:149]
	v_pk_add_f32 v[144:145], v[142:143], v[154:155]
	v_cvt_pk_bf16_f32 v142, v164, v165
	v_cvt_pk_bf16_f32 v143, v172, v173
	v_cvt_pk_bf16_f32 v144, v144, v145
	v_cvt_pk_bf16_f32 v145, v148, v149
	global_store_dwordx4 v[158:159], v[142:145], off offset:256
	ds_read_b64 v[142:143], v141 offset:256
	s_waitcnt lgkmcnt(0)
	v_pk_mul_f32 v[142:143], v[142:143], s[44:45] op_sel_hi:[1,0]
	s_nop 0
	v_fma_f32 v143, -v142, v142, v143
	v_max_f32_e32 v143, 0, v143
	v_add_f32_e32 v143, 0x3727c5ac, v143
	v_cmp_gt_f32_e32 vcc, s27, v143
	v_mul_f32_e32 v144, 0x4b800000, v143
	s_nop 0
	v_cndmask_b32_e32 v143, v143, v144, vcc
	v_rsq_f32_e32 v143, v143
	s_nop 0
	v_mul_f32_e32 v144, 0x45800000, v143
	v_cndmask_b32_e32 v148, v143, v144, vcc
	v_mul_f32_e64 v154, v142, -v148
	ds_read_b128 v[142:145], v140
	ds_read_b128 v[202:205], v140 offset:16
	s_waitcnt lgkmcnt(0)
	v_pk_mul_f32 v[144:145], v[144:145], v[154:155] op_sel_hi:[1,0]
	v_pk_mul_f32 v[142:143], v[142:143], v[154:155] op_sel_hi:[1,0]
	v_pk_fma_f32 v[164:165], v[96:97], v[148:149], v[144:145] op_sel_hi:[1,0,1]
	v_pk_fma_f32 v[158:159], v[94:95], v[148:149], v[142:143] op_sel_hi:[1,0,1]
	ds_read_b128 v[142:145], v140 offset:1024
	s_waitcnt lgkmcnt(0)
	v_pk_add_f32 v[164:165], v[144:145], v[164:165]
	v_pk_add_f32 v[158:159], v[142:143], v[158:159]
	v_pk_mul_f32 v[142:143], v[204:205], v[154:155] op_sel_hi:[1,0]
	v_pk_mul_f32 v[144:145], v[202:203], v[154:155] op_sel_hi:[1,0]
	v_pk_fma_f32 v[178:179], v[92:93], v[148:149], v[142:143] op_sel_hi:[1,0,1]
	v_pk_fma_f32 v[172:173], v[90:91], v[148:149], v[144:145] op_sel_hi:[1,0,1]
	ds_read_b128 v[142:145], v140 offset:1040
	s_waitcnt lgkmcnt(0)
; #define LAS __attribute__((address_space(3)))
; DI unsigned pk2(float a, float b) { typedef __bf16 bf2 __attribute__((ext_vector_type(2))); bf2 v; v[0] = (__bf16)a; v[1] = (__bf16)b; return __builtin_bit_cast(unsigned, v); }
;   template <int SECT>
;   DI void body(const f32x4 (&acc)[2][2][4][2], const pg8::Unit& u, int wr, int wc, int fr, int fq, LAS unsigned char* lds, int ui, int wid) const {
;     ...
;         const int row = u.pm * 256 + ai * 128 + wr * 64 + m * 16 + fr; float a, bb;
;         { typedef float f32x2_ __attribute__((ext_vector_type(2))); const f32x2_ sv = *(const LAS f32x2_*)(sl + ai * 128 + (m * 16 + fr_) * 2);
;           const float mu = sv.x * (1.0f / 1024.0f), var = fmaxf(sv.y * (1.0f / 1024.0f) - mu * mu, 0.f), rstd = rsqrtf(var + 1e-5f); a = rstd; bb = -rstd * mu; }
; #pragma unroll
;         for (int bj = 0; bj < 2; ++bj) {
;           const int col = col0 + bj * 128;
;           f32x4 v[2];
; #pragma unroll
;           for (int n = 0; n < 2; ++n) v[n] = acc[ai][bj][m][n] * a + (*(const LAS f32x4*)(cl + bj * 128 + 4 * n)) * bb + *(const LAS f32x4*)(cl + 256 + bj * 128 + 4 * n);
;           if (SECT < 0) { u32x4 w; w[0] = pk2(v[0][0], v[0][1]); w[1] = pk2(v[0][2], v[0][3]); w[2] = pk2(v[1][0], v[1][1]); w[3] = pk2(v[1][2], v[1][3]); *(u32x4*)(h + (size_t)row * ld + col) = w; }
	v_pk_add_f32 v[178:179], v[144:145], v[178:179]
	v_pk_add_f32 v[144:145], v[142:143], v[172:173]
	v_cvt_pk_bf16_f32 v142, v158, v159
	v_mad_i64_i32 v[158:159], s[28:29], v166, s30, 0
	v_lshl_add_u64 v[158:159], v[158:159], 1, s[10:11]
	v_cvt_pk_bf16_f32 v143, v164, v165
	v_cvt_pk_bf16_f32 v144, v144, v145
	v_cvt_pk_bf16_f32 v145, v178, v179
	v_lshl_add_u64 v[158:159], v[158:159], 0, v[138:139]
	global_store_dwordx4 v[158:159], v[142:145], off
	ds_read_b128 v[142:145], v140 offset:512
	s_waitcnt lgkmcnt(0)
	v_pk_mul_f32 v[144:145], v[144:145], v[154:155] op_sel_hi:[1,0]
	v_pk_mul_f32 v[142:143], v[142:143], v[154:155] op_sel_hi:[1,0]
	v_pk_fma_f32 v[172:173], v[88:89], v[148:149], v[144:145] op_sel_hi:[1,0,1]
	v_pk_fma_f32 v[164:165], v[86:87], v[148:149], v[142:143] op_sel_hi:[1,0,1]
	ds_read_b128 v[142:145], v140 offset:1536
	s_waitcnt lgkmcnt(0)
	v_pk_add_f32 v[172:173], v[144:145], v[172:173]
	v_pk_add_f32 v[164:165], v[142:143], v[164:165]
	ds_read_b128 v[142:145], v140 offset:528
	s_waitcnt lgkmcnt(0)
	v_pk_mul_f32 v[144:145], v[144:145], v[154:155] op_sel_hi:[1,0]
	v_pk_mul_f32 v[142:143], v[142:143], v[154:155] op_sel_hi:[1,0]
	s_nop 0
	v_pk_fma_f32 v[154:155], v[82:83], v[148:149], v[142:143] op_sel_hi:[1,0,1]
	v_pk_fma_f32 v[148:149], v[84:85], v[148:149], v[144:145] op_sel_hi:[1,0,1]
	ds_read_b128 v[142:145], v140 offset:1552
	s_waitcnt lgkmcnt(0)
	v_pk_add_f32 v[148:149], v[144:145], v[148:149]
	v_pk_add_f32 v[144:145], v[142:143], v[154:155]
	v_cvt_pk_bf16_f32 v142, v164, v165
	v_cvt_pk_bf16_f32 v143, v172, v173
	v_cvt_pk_bf16_f32 v144, v144, v145
	v_cvt_pk_bf16_f32 v145, v148, v149
	global_store_dwordx4 v[158:159], v[142:145], off offset:256
	ds_read_b64 v[142:143], v141 offset:384
	s_waitcnt lgkmcnt(0)
	v_pk_mul_f32 v[142:143], v[142:143], s[44:45] op_sel_hi:[1,0]
	s_nop 0
	v_fma_f32 v143, -v142, v142, v143
	v_max_f32_e32 v143, 0, v143
	v_add_f32_e32 v143, 0x3727c5ac, v143
	v_cmp_gt_f32_e32 vcc, s27, v143
	v_mul_f32_e32 v144, 0x4b800000, v143
	s_nop 0
	v_cndmask_b32_e32 v143, v143, v144, vcc
	v_rsq_f32_e32 v143, v143
	s_nop 0
	v_mul_f32_e32 v144, 0x45800000, v143
	v_cndmask_b32_e32 v148, v143, v144, vcc
	v_mul_f32_e64 v154, v142, -v148
	ds_read_b128 v[142:145], v140
	ds_read_b128 v[202:205], v140 offset:16
	s_waitcnt lgkmcnt(0)
	v_pk_mul_f32 v[144:145], v[144:145], v[154:155] op_sel_hi:[1,0]
	v_pk_mul_f32 v[142:143], v[142:143], v[154:155] op_sel_hi:[1,0]
	v_pk_fma_f32 v[164:165], v[80:81], v[148:149], v[144:145] op_sel_hi:[1,0,1]
	v_pk_fma_f32 v[158:159], v[78:79], v[148:149], v[142:143] op_sel_hi:[1,0,1]
	ds_read_b128 v[142:145], v140 offset:1024
	s_waitcnt lgkmcnt(0)
	v_pk_add_f32 v[164:165], v[144:145], v[164:165]
	v_pk_add_f32 v[158:159], v[142:143], v[158:159]
	v_pk_mul_f32 v[142:143], v[204:205], v[154:155] op_sel_hi:[1,0]
	v_pk_mul_f32 v[144:145], v[202:203], v[154:155] op_sel_hi:[1,0]
	v_pk_fma_f32 v[178:179], v[76:77], v[148:149], v[142:143] op_sel_hi:[1,0,1]
	v_pk_fma_f32 v[172:173], v[74:75], v[148:149], v[144:145] op_sel_hi:[1,0,1]
	ds_read_b128 v[142:145], v140 offset:1040
	s_waitcnt lgkmcnt(0)
	v_pk_add_f32 v[178:179], v[144:145], v[178:179]
	v_pk_add_f32 v[144:145], v[142:143], v[172:173]
	v_cvt_pk_bf16_f32 v142, v158, v159
	v_mad_i64_i32 v[158:159], s[28:29], v162, s30, 0
	v_lshl_add_u64 v[158:159], v[158:159], 1, s[10:11]
	v_cvt_pk_bf16_f32 v143, v164, v165
	v_cvt_pk_bf16_f32 v144, v144, v145
	v_cvt_pk_bf16_f32 v145, v178, v179
	v_lshl_add_u64 v[158:159], v[158:159], 0, v[138:139]
	global_store_dwordx4 v[158:159], v[142:145], off
	ds_read_b128 v[142:145], v140 offset:512
	s_waitcnt lgkmcnt(0)
	v_pk_mul_f32 v[144:145], v[144:145], v[154:155] op_sel_hi:[1,0]
	v_pk_mul_f32 v[142:143], v[142:143], v[154:155] op_sel_hi:[1,0]
	v_pk_fma_f32 v[172:173], v[72:73], v[148:149], v[144:145] op_sel_hi:[1,0,1]
	v_pk_fma_f32 v[164:165], v[70:71], v[148:149], v[142:143] op_sel_hi:[1,0,1]
	ds_read_b128 v[142:145], v140 offset:1536
	s_waitcnt lgkmcnt(0)
	v_pk_add_f32 v[172:173], v[144:145], v[172:173]
	v_pk_add_f32 v[164:165], v[142:143], v[164:165]
	ds_read_b128 v[142:145], v140 offset:528
	s_waitcnt lgkmcnt(0)
	v_pk_mul_f32 v[144:145], v[144:145], v[154:155] op_sel_hi:[1,0]
	v_pk_mul_f32 v[142:143], v[142:143], v[154:155] op_sel_hi:[1,0]
	s_nop 0
	v_pk_fma_f32 v[154:155], v[66:67], v[148:149], v[142:143] op_sel_hi:[1,0,1]
	v_pk_fma_f32 v[148:149], v[68:69], v[148:149], v[144:145] op_sel_hi:[1,0,1]
	ds_read_b128 v[142:145], v140 offset:1552
	s_waitcnt lgkmcnt(0)
	v_pk_add_f32 v[148:149], v[144:145], v[148:149]
	v_pk_add_f32 v[144:145], v[142:143], v[154:155]
	v_cvt_pk_bf16_f32 v142, v164, v165
	v_cvt_pk_bf16_f32 v143, v172, v173
	v_cvt_pk_bf16_f32 v144, v144, v145
	v_cvt_pk_bf16_f32 v145, v148, v149
	global_store_dwordx4 v[158:159], v[142:145], off offset:256
	ds_read_b64 v[142:143], v141 offset:512
	s_waitcnt lgkmcnt(0)
	v_pk_mul_f32 v[142:143], v[142:143], s[44:45] op_sel_hi:[1,0]
	s_nop 0
	v_fma_f32 v143, -v142, v142, v143
	v_max_f32_e32 v143, 0, v143
	v_add_f32_e32 v143, 0x3727c5ac, v143
	v_cmp_gt_f32_e32 vcc, s27, v143
	v_mul_f32_e32 v144, 0x4b800000, v143
	s_nop 0
	v_cndmask_b32_e32 v143, v143, v144, vcc
	v_rsq_f32_e32 v143, v143
	s_nop 0
	v_mul_f32_e32 v144, 0x45800000, v143
	v_cndmask_b32_e32 v148, v143, v144, vcc
	v_mul_f32_e64 v154, v142, -v148
	ds_read_b128 v[142:145], v140
	ds_read_b128 v[202:205], v140 offset:16
	s_waitcnt lgkmcnt(0)
	v_pk_mul_f32 v[144:145], v[144:145], v[154:155] op_sel_hi:[1,0]
	v_pk_mul_f32 v[142:143], v[142:143], v[154:155] op_sel_hi:[1,0]
	v_pk_fma_f32 v[164:165], v[64:65], v[148:149], v[144:145] op_sel_hi:[1,0,1]
	v_pk_fma_f32 v[158:159], v[62:63], v[148:149], v[142:143] op_sel_hi:[1,0,1]
	ds_read_b128 v[142:145], v140 offset:1024
	s_waitcnt lgkmcnt(0)
; #define LAS __attribute__((address_space(3)))
; DI unsigned pk2(float a, float b) { typedef __bf16 bf2 __attribute__((ext_vector_type(2))); bf2 v; v[0] = (__bf16)a; v[1] = (__bf16)b; return __builtin_bit_cast(unsigned, v); }
;   template <int SECT>
;   DI void body(const f32x4 (&acc)[2][2][4][2], const pg8::Unit& u, int wr, int wc, int fr, int fq, LAS unsigned char* lds, int ui, int wid) const {
;     ...
;         const int row = u.pm * 256 + ai * 128 + wr * 64 + m * 16 + fr; float a, bb;
;         { typedef float f32x2_ __attribute__((ext_vector_type(2))); const f32x2_ sv = *(const LAS f32x2_*)(sl + ai * 128 + (m * 16 + fr_) * 2);
;           const float mu = sv.x * (1.0f / 1024.0f), var = fmaxf(sv.y * (1.0f / 1024.0f) - mu * mu, 0.f), rstd = rsqrtf(var + 1e-5f); a = rstd; bb = -rstd * mu; }
; #pragma unroll
;         for (int bj = 0; bj < 2; ++bj) {
;           const int col = col0 + bj * 128;
;           f32x4 v[2];
; #pragma unroll
;           for (int n = 0; n < 2; ++n) v[n] = acc[ai][bj][m][n] * a + (*(const LAS f32x4*)(cl + bj * 128 + 4 * n)) * bb + *(const LAS f32x4*)(cl + 256 + bj * 128 + 4 * n);
;           if (SECT < 0) { u32x4 w; w[0] = pk2(v[0][0], v[0][1]); w[1] = pk2(v[0][2], v[0][3]); w[2] = pk2(v[1][0], v[1][1]); w[3] = pk2(v[1][2], v[1][3]); *(u32x4*)(h + (size_t)row * ld + col) = w; }
	v_pk_add_f32 v[164:165], v[144:145], v[164:165]
	v_pk_add_f32 v[158:159], v[142:143], v[158:159]
	v_pk_mul_f32 v[142:143], v[204:205], v[154:155] op_sel_hi:[1,0]
	v_pk_mul_f32 v[144:145], v[202:203], v[154:155] op_sel_hi:[1,0]
	v_pk_fma_f32 v[178:179], v[60:61], v[148:149], v[142:143] op_sel_hi:[1,0,1]
	v_pk_fma_f32 v[172:173], v[58:59], v[148:149], v[144:145] op_sel_hi:[1,0,1]
	ds_read_b128 v[142:145], v140 offset:1040
	s_waitcnt lgkmcnt(0)
	v_pk_add_f32 v[178:179], v[144:145], v[178:179]
	v_pk_add_f32 v[144:145], v[142:143], v[172:173]
	v_cvt_pk_bf16_f32 v142, v158, v159
	v_mad_i64_i32 v[158:159], s[28:29], v160, s30, 0
	v_lshl_add_u64 v[158:159], v[158:159], 1, s[10:11]
	v_cvt_pk_bf16_f32 v143, v164, v165
	v_cvt_pk_bf16_f32 v144, v144, v145
	v_cvt_pk_bf16_f32 v145, v178, v179
	v_lshl_add_u64 v[158:159], v[158:159], 0, v[138:139]
	global_store_dwordx4 v[158:159], v[142:145], off
	ds_read_b128 v[142:145], v140 offset:512
	s_waitcnt lgkmcnt(0)
	v_pk_mul_f32 v[144:145], v[144:145], v[154:155] op_sel_hi:[1,0]
	v_pk_mul_f32 v[142:143], v[142:143], v[154:155] op_sel_hi:[1,0]
	v_pk_fma_f32 v[172:173], v[56:57], v[148:149], v[144:145] op_sel_hi:[1,0,1]
	v_pk_fma_f32 v[164:165], v[54:55], v[148:149], v[142:143] op_sel_hi:[1,0,1]
	ds_read_b128 v[142:145], v140 offset:1536
	s_waitcnt lgkmcnt(0)
	v_pk_add_f32 v[172:173], v[144:145], v[172:173]
	v_pk_add_f32 v[164:165], v[142:143], v[164:165]
	ds_read_b128 v[142:145], v140 offset:528
	s_waitcnt lgkmcnt(0)
	v_pk_mul_f32 v[144:145], v[144:145], v[154:155] op_sel_hi:[1,0]
	v_pk_mul_f32 v[142:143], v[142:143], v[154:155] op_sel_hi:[1,0]
	s_nop 0
	v_pk_fma_f32 v[154:155], v[50:51], v[148:149], v[142:143] op_sel_hi:[1,0,1]
	v_pk_fma_f32 v[148:149], v[52:53], v[148:149], v[144:145] op_sel_hi:[1,0,1]
	ds_read_b128 v[142:145], v140 offset:1552
	s_waitcnt lgkmcnt(0)
	v_pk_add_f32 v[148:149], v[144:145], v[148:149]
	v_pk_add_f32 v[144:145], v[142:143], v[154:155]
	v_cvt_pk_bf16_f32 v142, v164, v165
	v_cvt_pk_bf16_f32 v143, v172, v173
	v_cvt_pk_bf16_f32 v144, v144, v145
	v_cvt_pk_bf16_f32 v145, v148, v149
	global_store_dwordx4 v[158:159], v[142:145], off offset:256
	ds_read_b64 v[142:143], v141 offset:640
	s_waitcnt lgkmcnt(0)
	v_pk_mul_f32 v[142:143], v[142:143], s[44:45] op_sel_hi:[1,0]
	s_nop 0
	v_fma_f32 v143, -v142, v142, v143
	v_max_f32_e32 v143, 0, v143
	v_add_f32_e32 v143, 0x3727c5ac, v143
	v_cmp_gt_f32_e32 vcc, s27, v143
	v_mul_f32_e32 v144, 0x4b800000, v143
	s_nop 0
	v_cndmask_b32_e32 v143, v143, v144, vcc
	v_rsq_f32_e32 v143, v143
	s_nop 0
	v_mul_f32_e32 v144, 0x45800000, v143
	v_cndmask_b32_e32 v148, v143, v144, vcc
	v_mul_f32_e64 v154, v142, -v148
	ds_read_b128 v[142:145], v140
	ds_read_b128 v[202:205], v140 offset:16
	s_waitcnt lgkmcnt(0)
	v_pk_mul_f32 v[144:145], v[144:145], v[154:155] op_sel_hi:[1,0]
	v_pk_mul_f32 v[142:143], v[142:143], v[154:155] op_sel_hi:[1,0]
	v_pk_fma_f32 v[164:165], v[48:49], v[148:149], v[144:145] op_sel_hi:[1,0,1]
	v_pk_fma_f32 v[158:159], v[46:47], v[148:149], v[142:143] op_sel_hi:[1,0,1]
	ds_read_b128 v[142:145], v140 offset:1024
	s_waitcnt lgkmcnt(0)
	v_pk_add_f32 v[164:165], v[144:145], v[164:165]
	v_pk_add_f32 v[158:159], v[142:143], v[158:159]
	v_pk_mul_f32 v[142:143], v[204:205], v[154:155] op_sel_hi:[1,0]
	v_pk_mul_f32 v[144:145], v[202:203], v[154:155] op_sel_hi:[1,0]
	v_pk_fma_f32 v[178:179], v[44:45], v[148:149], v[142:143] op_sel_hi:[1,0,1]
	v_pk_fma_f32 v[172:173], v[42:43], v[148:149], v[144:145] op_sel_hi:[1,0,1]
	ds_read_b128 v[142:145], v140 offset:1040
	s_waitcnt lgkmcnt(0)
	v_pk_add_f32 v[178:179], v[144:145], v[178:179]
	v_pk_add_f32 v[144:145], v[142:143], v[172:173]
	v_cvt_pk_bf16_f32 v142, v158, v159
	v_mad_i64_i32 v[158:159], s[28:29], v156, s30, 0
	v_lshl_add_u64 v[158:159], v[158:159], 1, s[10:11]
	v_cvt_pk_bf16_f32 v143, v164, v165
	v_cvt_pk_bf16_f32 v144, v144, v145
	v_cvt_pk_bf16_f32 v145, v178, v179
	v_lshl_add_u64 v[158:159], v[158:159], 0, v[138:139]
	global_store_dwordx4 v[158:159], v[142:145], off
	ds_read_b128 v[142:145], v140 offset:512
	s_waitcnt lgkmcnt(0)
	v_pk_mul_f32 v[144:145], v[144:145], v[154:155] op_sel_hi:[1,0]
	v_pk_mul_f32 v[142:143], v[142:143], v[154:155] op_sel_hi:[1,0]
	v_pk_fma_f32 v[172:173], v[40:41], v[148:149], v[144:145] op_sel_hi:[1,0,1]
	v_pk_fma_f32 v[164:165], v[38:39], v[148:149], v[142:143] op_sel_hi:[1,0,1]
	ds_read_b128 v[142:145], v140 offset:1536
	s_waitcnt lgkmcnt(0)
	v_pk_add_f32 v[172:173], v[144:145], v[172:173]
	v_pk_add_f32 v[164:165], v[142:143], v[164:165]
	ds_read_b128 v[142:145], v140 offset:528
	s_waitcnt lgkmcnt(0)
	v_pk_mul_f32 v[144:145], v[144:145], v[154:155] op_sel_hi:[1,0]
	v_pk_mul_f32 v[142:143], v[142:143], v[154:155] op_sel_hi:[1,0]
	s_nop 0
	v_pk_fma_f32 v[154:155], v[34:35], v[148:149], v[142:143] op_sel_hi:[1,0,1]
	v_pk_fma_f32 v[148:149], v[36:37], v[148:149], v[144:145] op_sel_hi:[1,0,1]
	ds_read_b128 v[142:145], v140 offset:1552
	s_waitcnt lgkmcnt(0)
	v_pk_add_f32 v[148:149], v[144:145], v[148:149]
	v_pk_add_f32 v[144:145], v[142:143], v[154:155]
	v_cvt_pk_bf16_f32 v142, v164, v165
	v_cvt_pk_bf16_f32 v143, v172, v173
	v_cvt_pk_bf16_f32 v144, v144, v145
	v_cvt_pk_bf16_f32 v145, v148, v149
	global_store_dwordx4 v[158:159], v[142:145], off offset:256
	ds_read_b64 v[142:143], v141 offset:768
	s_waitcnt lgkmcnt(0)
	v_pk_mul_f32 v[142:143], v[142:143], s[44:45] op_sel_hi:[1,0]
	s_nop 0
	v_fma_f32 v143, -v142, v142, v143
	v_max_f32_e32 v143, 0, v143
	v_add_f32_e32 v143, 0x3727c5ac, v143
	v_cmp_gt_f32_e32 vcc, s27, v143
	v_mul_f32_e32 v144, 0x4b800000, v143
	s_nop 0
	v_cndmask_b32_e32 v143, v143, v144, vcc
	v_rsq_f32_e32 v143, v143
	s_nop 0
	v_mul_f32_e32 v144, 0x45800000, v143
	v_cndmask_b32_e32 v148, v143, v144, vcc
	v_mul_f32_e64 v154, v142, -v148
	ds_read_b128 v[142:145], v140
	ds_read_b128 v[202:205], v140 offset:16
	s_waitcnt lgkmcnt(0)
; #define LAS __attribute__((address_space(3)))
; DI unsigned pk2(float a, float b) { typedef __bf16 bf2 __attribute__((ext_vector_type(2))); bf2 v; v[0] = (__bf16)a; v[1] = (__bf16)b; return __builtin_bit_cast(unsigned, v); }
;   template <int SECT>
;   DI void body(const f32x4 (&acc)[2][2][4][2], const pg8::Unit& u, int wr, int wc, int fr, int fq, LAS unsigned char* lds, int ui, int wid) const {
;     ...
;         const int row = u.pm * 256 + ai * 128 + wr * 64 + m * 16 + fr; float a, bb;
;         { typedef float f32x2_ __attribute__((ext_vector_type(2))); const f32x2_ sv = *(const LAS f32x2_*)(sl + ai * 128 + (m * 16 + fr_) * 2);
;           const float mu = sv.x * (1.0f / 1024.0f), var = fmaxf(sv.y * (1.0f / 1024.0f) - mu * mu, 0.f), rstd = rsqrtf(var + 1e-5f); a = rstd; bb = -rstd * mu; }
; #pragma unroll
;         for (int bj = 0; bj < 2; ++bj) {
;           const int col = col0 + bj * 128;
;           f32x4 v[2];
; #pragma unroll
;           for (int n = 0; n < 2; ++n) v[n] = acc[ai][bj][m][n] * a + (*(const LAS f32x4*)(cl + bj * 128 + 4 * n)) * bb + *(const LAS f32x4*)(cl + 256 + bj * 128 + 4 * n);
;           if (SECT < 0) { u32x4 w; w[0] = pk2(v[0][0], v[0][1]); w[1] = pk2(v[0][2], v[0][3]); w[2] = pk2(v[1][0], v[1][1]); w[3] = pk2(v[1][2], v[1][3]); *(u32x4*)(h + (size_t)row * ld + col) = w; }
	v_pk_mul_f32 v[144:145], v[144:145], v[154:155] op_sel_hi:[1,0]
	v_pk_mul_f32 v[142:143], v[142:143], v[154:155] op_sel_hi:[1,0]
	v_pk_fma_f32 v[164:165], v[30:31], v[148:149], v[144:145] op_sel_hi:[1,0,1]
	v_pk_fma_f32 v[158:159], v[28:29], v[148:149], v[142:143] op_sel_hi:[1,0,1]
	ds_read_b128 v[142:145], v140 offset:1024
	s_waitcnt lgkmcnt(0)
	v_pk_add_f32 v[164:165], v[144:145], v[164:165]
	v_pk_add_f32 v[158:159], v[142:143], v[158:159]
	v_pk_mul_f32 v[142:143], v[204:205], v[154:155] op_sel_hi:[1,0]
	v_pk_mul_f32 v[144:145], v[202:203], v[154:155] op_sel_hi:[1,0]
	v_pk_fma_f32 v[178:179], v[26:27], v[148:149], v[142:143] op_sel_hi:[1,0,1]
	v_pk_fma_f32 v[172:173], v[24:25], v[148:149], v[144:145] op_sel_hi:[1,0,1]
	ds_read_b128 v[142:145], v140 offset:1040
	s_waitcnt lgkmcnt(0)
	v_pk_add_f32 v[178:179], v[144:145], v[178:179]
	v_pk_add_f32 v[144:145], v[142:143], v[172:173]
	v_cvt_pk_bf16_f32 v142, v158, v159
	v_mad_i64_i32 v[158:159], s[28:29], v152, s30, 0
	v_lshl_add_u64 v[158:159], v[158:159], 1, s[10:11]
	v_cvt_pk_bf16_f32 v143, v164, v165
	v_cvt_pk_bf16_f32 v144, v144, v145
	v_cvt_pk_bf16_f32 v145, v178, v179
	v_lshl_add_u64 v[158:159], v[158:159], 0, v[138:139]
	global_store_dwordx4 v[158:159], v[142:145], off
	ds_read_b128 v[142:145], v140 offset:512
	s_waitcnt lgkmcnt(0)
	v_pk_mul_f32 v[144:145], v[144:145], v[154:155] op_sel_hi:[1,0]
	v_pk_mul_f32 v[142:143], v[142:143], v[154:155] op_sel_hi:[1,0]
	v_pk_fma_f32 v[172:173], v[22:23], v[148:149], v[144:145] op_sel_hi:[1,0,1]
	v_pk_fma_f32 v[164:165], v[20:21], v[148:149], v[142:143] op_sel_hi:[1,0,1]
	ds_read_b128 v[142:145], v140 offset:1536
	s_waitcnt lgkmcnt(0)
	v_pk_add_f32 v[172:173], v[144:145], v[172:173]
	v_pk_add_f32 v[164:165], v[142:143], v[164:165]
	ds_read_b128 v[142:145], v140 offset:528
	s_waitcnt lgkmcnt(0)
	v_pk_mul_f32 v[144:145], v[144:145], v[154:155] op_sel_hi:[1,0]
	v_pk_mul_f32 v[142:143], v[142:143], v[154:155] op_sel_hi:[1,0]
	s_nop 0
	v_pk_fma_f32 v[154:155], v[16:17], v[148:149], v[142:143] op_sel_hi:[1,0,1]
	v_pk_fma_f32 v[148:149], v[18:19], v[148:149], v[144:145] op_sel_hi:[1,0,1]
	ds_read_b128 v[142:145], v140 offset:1552
	s_waitcnt lgkmcnt(0)
	v_pk_add_f32 v[148:149], v[144:145], v[148:149]
	v_pk_add_f32 v[144:145], v[142:143], v[154:155]
	v_cvt_pk_bf16_f32 v142, v164, v165
	v_cvt_pk_bf16_f32 v143, v172, v173
	v_cvt_pk_bf16_f32 v144, v144, v145
	v_cvt_pk_bf16_f32 v145, v148, v149
	global_store_dwordx4 v[158:159], v[142:145], off offset:256
	ds_read_b64 v[142:143], v141 offset:896
	s_waitcnt lgkmcnt(0)
	v_pk_mul_f32 v[142:143], v[142:143], s[44:45] op_sel_hi:[1,0]
	s_nop 0
	v_fma_f32 v141, -v142, v142, v143
	v_max_f32_e32 v141, 0, v141
	v_add_f32_e32 v141, 0x3727c5ac, v141
	v_cmp_gt_f32_e32 vcc, s27, v141
	v_mul_f32_e32 v143, 0x4b800000, v141
	s_nop 0
	v_cndmask_b32_e32 v141, v141, v143, vcc
	v_rsq_f32_e32 v141, v141
	s_nop 0
	v_mul_f32_e32 v143, 0x45800000, v141
	v_cndmask_b32_e32 v148, v141, v143, vcc
	v_mul_f32_e64 v154, v142, -v148
	ds_read_b128 v[142:145], v140
	ds_read_b128 v[202:205], v140 offset:16
	s_waitcnt lgkmcnt(0)
	v_pk_mul_f32 v[144:145], v[144:145], v[154:155] op_sel_hi:[1,0]
	v_pk_mul_f32 v[142:143], v[142:143], v[154:155] op_sel_hi:[1,0]
	v_pk_fma_f32 v[164:165], v[14:15], v[148:149], v[144:145] op_sel_hi:[1,0,1]
	v_pk_fma_f32 v[158:159], v[12:13], v[148:149], v[142:143] op_sel_hi:[1,0,1]
	ds_read_b128 v[142:145], v140 offset:1024
	s_waitcnt lgkmcnt(0)
	v_pk_add_f32 v[164:165], v[144:145], v[164:165]
	v_pk_add_f32 v[158:159], v[142:143], v[158:159]
	v_pk_mul_f32 v[142:143], v[204:205], v[154:155] op_sel_hi:[1,0]
	v_pk_mul_f32 v[144:145], v[202:203], v[154:155] op_sel_hi:[1,0]
	v_pk_fma_f32 v[178:179], v[10:11], v[148:149], v[142:143] op_sel_hi:[1,0,1]
	v_pk_fma_f32 v[172:173], v[8:9], v[148:149], v[144:145] op_sel_hi:[1,0,1]
	ds_read_b128 v[142:145], v140 offset:1040
	s_waitcnt lgkmcnt(0)
	v_pk_add_f32 v[178:179], v[144:145], v[178:179]
	v_pk_add_f32 v[144:145], v[142:143], v[172:173]
	v_cvt_pk_bf16_f32 v142, v158, v159
	v_mad_i64_i32 v[158:159], s[28:29], v150, s30, 0
	v_lshl_add_u64 v[158:159], v[158:159], 1, s[10:11]
	v_cvt_pk_bf16_f32 v143, v164, v165
	v_cvt_pk_bf16_f32 v144, v144, v145
	v_cvt_pk_bf16_f32 v145, v178, v179
	v_lshl_add_u64 v[158:159], v[158:159], 0, v[138:139]
	global_store_dwordx4 v[158:159], v[142:145], off
	ds_read_b128 v[142:145], v140 offset:512
	s_mov_b64 s[28:29], 0
	s_waitcnt lgkmcnt(0)
	v_pk_mul_f32 v[142:143], v[142:143], v[154:155] op_sel_hi:[1,0]
	v_pk_mul_f32 v[138:139], v[144:145], v[154:155] op_sel_hi:[1,0]
	v_pk_fma_f32 v[164:165], v[4:5], v[148:149], v[142:143] op_sel_hi:[1,0,1]
	ds_read_b128 v[142:145], v140 offset:1536
	v_pk_fma_f32 v[138:139], v[6:7], v[148:149], v[138:139] op_sel_hi:[1,0,1]
	s_waitcnt lgkmcnt(0)
	v_pk_add_f32 v[164:165], v[142:143], v[164:165]
	v_pk_add_f32 v[172:173], v[144:145], v[138:139]
	ds_read_b128 v[142:145], v140 offset:528
	s_waitcnt lgkmcnt(0)
	v_pk_mul_f32 v[138:139], v[144:145], v[154:155] op_sel_hi:[1,0]
	s_nop 0
	v_pk_fma_f32 v[144:145], v[2:3], v[148:149], v[138:139] op_sel_hi:[1,0,1]
	ds_read_b128 v[138:141], v140 offset:1552
	v_pk_mul_f32 v[142:143], v[142:143], v[154:155] op_sel_hi:[1,0]
	s_waitcnt lgkmcnt(0)
	v_pk_add_f32 v[144:145], v[140:141], v[144:145]
	v_pk_fma_f32 v[142:143], v[0:1], v[148:149], v[142:143] op_sel_hi:[1,0,1]
	s_nop 0
	v_pk_add_f32 v[140:141], v[138:139], v[142:143]
	v_cvt_pk_bf16_f32 v138, v164, v165
	v_cvt_pk_bf16_f32 v139, v172, v173
	v_cvt_pk_bf16_f32 v140, v140, v141
	v_cvt_pk_bf16_f32 v141, v144, v145
	global_store_dwordx4 v[158:159], v[138:141], off offset:256

; #define PG8_STAGE(bufoff, gbase, voff) do { _Pragma("unroll") for (int _i = 0; _i < 2; ++_i) \
;     __builtin_amdgcn_global_load_lds((const unsigned*)((const char*)(gbase) + (voff)[_i]), (LAS unsigned*)(lds + (bufoff) + ldsw + _i * 8192), 16, 0, 0); } while (0)
; #define PG8_LDA(dst, b, h) do { _Pragma("unroll") for (int m = 0; m < 4; ++m) _Pragma("unroll") for (int k = 0; k < 2; ++k) dst[m][k] = *(const LAS bf16x8*)(lds + PG8_SA(b, h) + aoff + m * 2048 + k * 1024); } while (0)
; #define PG8_LDB(dst, b, h) do { _Pragma("unroll") for (int n = 0; n < 2; ++n) _Pragma("unroll") for (int k = 0; k < 2; ++k) dst[n][k] = *(const LAS bf16x8*)(lds + PG8_SB(b, h) + boff + n * 2048 + k * 1024); } while (0)
; #define PG8_WAIT_V(n) asm volatile("s_waitcnt vmcnt(" #n ")" ::: "memory")
; #define PG8_WAIT_L(n) asm volatile("s_waitcnt lgkmcnt(" #n ")" ::: "memory")
; #define PG8_BAR __builtin_amdgcn_s_barrier()
; #define PG8_SCHED __builtin_amdgcn_sched_barrier(0)
; template <class Epi>
; DI void gemm_phase(int wv, LAS unsigned char* lds, const Gemm g, const StaticOrder& S, const Epi& E) {
;     ...
;       PG8_LDB(B0, 0, 0); PG8_SCHED; PG8_LDA(At, 0, 0); PG8_STAGE(PG8_SA(1, 1), a1 + hstep, voffA);
;       PG8_WAIT_L(8); PG8_BAR; PG8_WAIT_L(0); PG8_MMA(0, 0, At, B0); PG8_BAR; PG8_SCHED;
;       PG8_LDB(B1, 0, 1); PG8_STAGE(PG8_SB(0, 0), b2, voffA);
;       PG8_BAR; PG8_WAIT_L(0); PG8_MMA(0, 1, At, B1); PG8_BAR;
;       PG8_LDA(At, 0, 1); PG8_STAGE(PG8_SA(0, 0), a2, voffA);
;       PG8_BAR; PG8_WAIT_L(0); PG8_MMA(1, 0, At, B0); PG8_BAR; PG8_SCHED;
;       PG8_STAGE(PG8_SB(0, 1), b2 + hstep, voffA);
;       PG8_WAIT_V(6); PG8_BAR; PG8_MMA(1, 1, At, B1); PG8_BAR;
.Lgprio_c:
.LBB0_890:
	s_add_i32 vcc_hi, s34, 2
	s_add_u32 s36, s30, 0x80
	s_addc_u32 s35, s31, 0
	s_add_i32 s41, 0, 0x10000
	v_add_u32_e32 v138, s41, v246
	ds_read_b128 v[58:61], v138
	ds_read_b128 v[66:69], v138 offset:1024
	ds_read_b128 v[130:133], v138 offset:2048
	ds_read_b128 v[138:141], v138 offset:3072
	s_cmp_eq_u32 s60, s34
	s_cselect_b32 s34, s0, s36
	s_cselect_b32 s35, s1, s35
	s_cselect_b32 s37, s29, vcc_lo
	s_cselect_b32 s36, s28, s95
	v_lshl_add_u64 v[178:179], s[30:31], 0, v[206:207]
	s_add_i32 m0, s62, 0xc000
	ds_read_b128 v[142:145], v248
	ds_read_b128 v[146:149], v248 offset:1024
	ds_read_b128 v[150:153], v248 offset:2048
	ds_read_b128 v[154:157], v248 offset:3072
	ds_read_b128 v[158:161], v248 offset:4096
	ds_read_b128 v[166:169], v248 offset:5120
	ds_read_b128 v[170:173], v248 offset:6144
	ds_read_b128 v[174:177], v248 offset:7168
	global_load_lds_dwordx4 v[178:179], off
	v_lshl_add_u64 v[178:179], s[30:31], 0, v[208:209]
	s_add_i32 m0, s62, 0xe000
	s_nop 0
	global_load_lds_dwordx4 v[178:179], off
	s_waitcnt lgkmcnt(8)
	s_barrier
	s_waitcnt lgkmcnt(0)
	v_mfma_f32_16x16x32_f16 v[162:165], v[58:61], v[142:145], v[162:165]
	v_mfma_f32_16x16x32_f16 v[134:137], v[130:133], v[142:145], v[134:137]
	v_mfma_f32_16x16x32_f16 v[118:121], v[58:61], v[150:153], v[118:121]
	v_mfma_f32_16x16x32_f16 v[114:117], v[130:133], v[150:153], v[114:117]
	v_mfma_f32_16x16x32_f16 v[102:105], v[58:61], v[158:161], v[102:105]
	v_mfma_f32_16x16x32_f16 v[98:101], v[130:133], v[158:161], v[98:101]
	v_mfma_f32_16x16x32_f16 v[86:89], v[58:61], v[170:173], v[86:89]
	v_mfma_f32_16x16x32_f16 v[82:85], v[130:133], v[170:173], v[82:85]
	v_mfma_f32_16x16x32_f16 v[162:165], v[66:69], v[146:149], v[162:165]
	v_mfma_f32_16x16x32_f16 v[134:137], v[138:141], v[146:149], v[134:137]
	v_mfma_f32_16x16x32_f16 v[118:121], v[66:69], v[154:157], v[118:121]
	v_mfma_f32_16x16x32_f16 v[114:117], v[138:141], v[154:157], v[114:117]
	v_mfma_f32_16x16x32_f16 v[102:105], v[66:69], v[166:169], v[102:105]
	v_mfma_f32_16x16x32_f16 v[98:101], v[138:141], v[166:169], v[98:101]
	v_mfma_f32_16x16x32_f16 v[86:89], v[66:69], v[174:177], v[86:89]
	v_mfma_f32_16x16x32_f16 v[82:85], v[138:141], v[174:177], v[82:85]
	s_barrier
	s_add_i32 s42, 0, 0x14000
	s_add_i32 s41, s41, s57
	v_add_u32_e32 v190, s42, v246
	v_lshl_add_u64 v[210:211], s[36:37], 0, v[202:203]
	s_mov_b32 m0, s41
	ds_read_b128 v[178:181], v190
	ds_read_b128 v[182:185], v190 offset:1024
	ds_read_b128 v[186:189], v190 offset:2048
	ds_read_b128 v[190:193], v190 offset:3072
	global_load_lds_dwordx4 v[210:211], off
	v_lshl_add_u64 v[212:213], s[36:37], 0, v[204:205]
	s_add_i32 m0, s41, 0x2000
	s_nop 0
	global_load_lds_dwordx4 v[212:213], off
	s_barrier
	s_waitcnt lgkmcnt(0)
	v_mfma_f32_16x16x32_f16 v[126:129], v[178:181], v[142:145], v[126:129]
	v_mfma_f32_16x16x32_f16 v[122:125], v[186:189], v[142:145], v[122:125]
	v_mfma_f32_16x16x32_f16 v[110:113], v[178:181], v[150:153], v[110:113]
	v_mfma_f32_16x16x32_f16 v[106:109], v[186:189], v[150:153], v[106:109]
	v_mfma_f32_16x16x32_f16 v[94:97], v[178:181], v[158:161], v[94:97]
	v_mfma_f32_16x16x32_f16 v[90:93], v[186:189], v[158:161], v[90:93]
	v_mfma_f32_16x16x32_f16 v[78:81], v[178:181], v[170:173], v[78:81]
	v_mfma_f32_16x16x32_f16 v[74:77], v[186:189], v[170:173], v[74:77]
	v_mfma_f32_16x16x32_f16 v[126:129], v[182:185], v[146:149], v[126:129]
	v_mfma_f32_16x16x32_f16 v[122:125], v[190:193], v[146:149], v[122:125]
	v_mfma_f32_16x16x32_f16 v[110:113], v[182:185], v[154:157], v[110:113]
	v_mfma_f32_16x16x32_f16 v[106:109], v[190:193], v[154:157], v[106:109]
	v_mfma_f32_16x16x32_f16 v[94:97], v[182:185], v[166:169], v[94:97]
	v_mfma_f32_16x16x32_f16 v[90:93], v[190:193], v[166:169], v[90:93]
	v_mfma_f32_16x16x32_f16 v[78:81], v[182:185], v[174:177], v[78:81]
	v_mfma_f32_16x16x32_f16 v[74:77], v[190:193], v[174:177], v[74:77]
	s_mov_b32 m0, s62
	v_lshl_add_u64 v[214:215], s[34:35], 0, v[202:203]
	s_barrier
	ds_read_b128 v[142:145], v248 offset:16384
	ds_read_b128 v[146:149], v248 offset:17408
	ds_read_b128 v[150:153], v248 offset:18432
	ds_read_b128 v[154:157], v248 offset:19456
	ds_read_b128 v[158:161], v248 offset:20480
	ds_read_b128 v[166:169], v248 offset:21504
	ds_read_b128 v[170:173], v248 offset:22528
	ds_read_b128 v[174:177], v248 offset:23552
	global_load_lds_dwordx4 v[214:215], off
	v_lshl_add_u64 v[216:217], s[34:35], 0, v[204:205]
	s_mov_b32 m0, s64
	s_nop 0
	global_load_lds_dwordx4 v[216:217], off
	s_barrier
	s_waitcnt lgkmcnt(0)
	v_mfma_f32_16x16x32_f16 v[70:73], v[58:61], v[142:145], v[70:73]
	v_mfma_f32_16x16x32_f16 v[62:65], v[130:133], v[142:145], v[62:65]
	v_mfma_f32_16x16x32_f16 v[46:49], v[58:61], v[150:153], v[46:49]
	v_mfma_f32_16x16x32_f16 v[42:45], v[130:133], v[150:153], v[42:45]
	v_mfma_f32_16x16x32_f16 v[28:31], v[58:61], v[158:161], v[28:31]
	v_mfma_f32_16x16x32_f16 v[24:27], v[130:133], v[158:161], v[24:27]
	v_mfma_f32_16x16x32_f16 v[12:15], v[58:61], v[170:173], v[12:15]
	v_mfma_f32_16x16x32_f16 v[8:11], v[130:133], v[170:173], v[8:11]
	v_mfma_f32_16x16x32_f16 v[70:73], v[66:69], v[146:149], v[70:73]
	v_mfma_f32_16x16x32_f16 v[62:65], v[138:141], v[146:149], v[62:65]
	v_mfma_f32_16x16x32_f16 v[46:49], v[66:69], v[154:157], v[46:49]
	v_mfma_f32_16x16x32_f16 v[42:45], v[138:141], v[154:157], v[42:45]
	v_mfma_f32_16x16x32_f16 v[28:31], v[66:69], v[166:169], v[28:31]
	v_mfma_f32_16x16x32_f16 v[24:27], v[138:141], v[166:169], v[24:27]
	v_mfma_f32_16x16x32_f16 v[12:15], v[66:69], v[174:177], v[12:15]
	v_mfma_f32_16x16x32_f16 v[8:11], v[138:141], v[174:177], v[8:11]
	s_barrier
; #define PG8_STAGE(bufoff, gbase, voff) do { _Pragma("unroll") for (int _i = 0; _i < 2; ++_i) \
;     __builtin_amdgcn_global_load_lds((const unsigned*)((const char*)(gbase) + (voff)[_i]), (LAS unsigned*)(lds + (bufoff) + ldsw + _i * 8192), 16, 0, 0); } while (0)
; #define PG8_LDA(dst, b, h) do { _Pragma("unroll") for (int m = 0; m < 4; ++m) _Pragma("unroll") for (int k = 0; k < 2; ++k) dst[m][k] = *(const LAS bf16x8*)(lds + PG8_SA(b, h) + aoff + m * 2048 + k * 1024); } while (0)
; #define PG8_LDB(dst, b, h) do { _Pragma("unroll") for (int n = 0; n < 2; ++n) _Pragma("unroll") for (int k = 0; k < 2; ++k) dst[n][k] = *(const LAS bf16x8*)(lds + PG8_SB(b, h) + boff + n * 2048 + k * 1024); } while (0)
; #define PG8_WAIT_V(n) asm volatile("s_waitcnt vmcnt(" #n ")" ::: "memory")
; #define PG8_WAIT_L(n) asm volatile("s_waitcnt lgkmcnt(" #n ")" ::: "memory")
; #define PG8_BAR __builtin_amdgcn_s_barrier()
; #define PG8_SCHED __builtin_amdgcn_sched_barrier(0)
; template <class Epi>
; DI void gemm_phase(int wv, LAS unsigned char* lds, const Gemm g, const StaticOrder& S, const Epi& E) {
;     ...
;       PG8_STAGE(PG8_SB(0, 1), b2 + hstep, voffA);
;       PG8_WAIT_V(6); PG8_BAR; PG8_MMA(1, 1, At, B1); PG8_BAR;
;       PG8_LDB(B0, 1, 0); PG8_SCHED; PG8_LDA(At, 1, 0); PG8_STAGE(PG8_SA(0, 1), a2 + hstep, voffA);
;       PG8_WAIT_L(8); PG8_BAR; PG8_WAIT_L(0); PG8_MMA(0, 0, At, B0); PG8_BAR; PG8_SCHED;
;       PG8_LDB(B1, 1, 1); PG8_STAGE(PG8_SB(1, 0), b3, voffA);
;       PG8_BAR; PG8_WAIT_L(0); PG8_MMA(0, 1, At, B1); PG8_BAR;
;       PG8_LDA(At, 1, 1); PG8_STAGE(PG8_SA(1, 0), a3, voffA);
;       PG8_BAR; PG8_WAIT_L(0); PG8_MMA(1, 0, At, B0); PG8_BAR; PG8_SCHED;
	s_add_u32 s36, s36, s84
	s_addc_u32 s37, s37, 0
	s_add_i32 s41, s42, s57
	v_lshl_add_u64 v[218:219], s[36:37], 0, v[202:203]
	s_mov_b32 m0, s41
	v_lshl_add_u64 v[220:221], s[36:37], 0, v[204:205]
	global_load_lds_dwordx4 v[218:219], off
	s_add_i32 m0, s41, 0x2000
	s_nop 0
	global_load_lds_dwordx4 v[220:221], off
	s_waitcnt vmcnt(6)
	s_barrier
	v_mfma_f32_16x16x32_f16 v[54:57], v[178:181], v[142:145], v[54:57]
	v_mfma_f32_16x16x32_f16 v[50:53], v[186:189], v[142:145], v[50:53]
	v_mfma_f32_16x16x32_f16 v[38:41], v[178:181], v[150:153], v[38:41]
	v_mfma_f32_16x16x32_f16 v[34:37], v[186:189], v[150:153], v[34:37]
	v_mfma_f32_16x16x32_f16 v[20:23], v[178:181], v[158:161], v[20:23]
	v_mfma_f32_16x16x32_f16 v[16:19], v[186:189], v[158:161], v[16:19]
	v_mfma_f32_16x16x32_f16 v[4:7], v[178:181], v[170:173], v[4:7]
	v_mfma_f32_16x16x32_f16 v[0:3], v[186:189], v[170:173], v[0:3]
	v_mfma_f32_16x16x32_f16 v[54:57], v[182:185], v[146:149], v[54:57]
	v_mfma_f32_16x16x32_f16 v[50:53], v[190:193], v[146:149], v[50:53]
	v_mfma_f32_16x16x32_f16 v[38:41], v[182:185], v[154:157], v[38:41]
	v_mfma_f32_16x16x32_f16 v[34:37], v[190:193], v[154:157], v[34:37]
	v_mfma_f32_16x16x32_f16 v[20:23], v[182:185], v[166:169], v[20:23]
	v_mfma_f32_16x16x32_f16 v[16:19], v[190:193], v[166:169], v[16:19]
	v_mfma_f32_16x16x32_f16 v[4:7], v[182:185], v[174:177], v[4:7]
	v_mfma_f32_16x16x32_f16 v[0:3], v[190:193], v[174:177], v[0:3]
	s_add_i32 s36, 0, 0x18000
	v_add_u32_e32 v138, s36, v246
	s_barrier
	ds_read_b128 v[58:61], v138
	ds_read_b128 v[66:69], v138 offset:1024
	ds_read_b128 v[130:133], v138 offset:2048
	ds_read_b128 v[138:141], v138 offset:3072
	s_add_u32 s34, s34, s84
	s_addc_u32 s35, s35, 0
	s_mov_b32 m0, s65
	v_lshl_add_u64 v[178:179], s[34:35], 0, v[202:203]
	ds_read_b128 v[142:145], v248 offset:32768
	ds_read_b128 v[146:149], v248 offset:33792
	ds_read_b128 v[150:153], v248 offset:34816
	ds_read_b128 v[154:157], v248 offset:35840
	ds_read_b128 v[158:161], v248 offset:36864
	ds_read_b128 v[166:169], v248 offset:37888
	ds_read_b128 v[170:173], v248 offset:38912
	ds_read_b128 v[174:177], v248 offset:39936
	global_load_lds_dwordx4 v[178:179], off
	v_lshl_add_u64 v[178:179], s[34:35], 0, v[204:205]
	s_mov_b32 m0, s70
	s_nop 0
	global_load_lds_dwordx4 v[178:179], off
	s_waitcnt lgkmcnt(8)
	s_barrier
	s_waitcnt lgkmcnt(0)
	v_mfma_f32_16x16x32_f16 v[162:165], v[58:61], v[142:145], v[162:165]
	v_mfma_f32_16x16x32_f16 v[134:137], v[130:133], v[142:145], v[134:137]
	v_mfma_f32_16x16x32_f16 v[118:121], v[58:61], v[150:153], v[118:121]
	v_mfma_f32_16x16x32_f16 v[114:117], v[130:133], v[150:153], v[114:117]
	v_mfma_f32_16x16x32_f16 v[102:105], v[58:61], v[158:161], v[102:105]
	v_mfma_f32_16x16x32_f16 v[98:101], v[130:133], v[158:161], v[98:101]
	v_mfma_f32_16x16x32_f16 v[86:89], v[58:61], v[170:173], v[86:89]
	v_mfma_f32_16x16x32_f16 v[82:85], v[130:133], v[170:173], v[82:85]
	v_mfma_f32_16x16x32_f16 v[162:165], v[66:69], v[146:149], v[162:165]
	v_mfma_f32_16x16x32_f16 v[134:137], v[138:141], v[146:149], v[134:137]
	v_mfma_f32_16x16x32_f16 v[118:121], v[66:69], v[154:157], v[118:121]
	v_mfma_f32_16x16x32_f16 v[114:117], v[138:141], v[154:157], v[114:117]
	v_mfma_f32_16x16x32_f16 v[102:105], v[66:69], v[166:169], v[102:105]
	v_mfma_f32_16x16x32_f16 v[98:101], v[138:141], v[166:169], v[98:101]
	v_mfma_f32_16x16x32_f16 v[86:89], v[66:69], v[174:177], v[86:89]
	v_mfma_f32_16x16x32_f16 v[82:85], v[138:141], v[174:177], v[82:85]
	s_barrier
	s_add_i32 s34, 0, 0x1c000
	s_add_i32 s35, s36, s57
	v_add_u32_e32 v190, s34, v246
	v_lshl_add_u64 v[210:211], v[210:211], 0, s[2:3]
	s_mov_b32 m0, s35
	ds_read_b128 v[178:181], v190
	ds_read_b128 v[182:185], v190 offset:1024
	ds_read_b128 v[186:189], v190 offset:2048
	ds_read_b128 v[190:193], v190 offset:3072
	global_load_lds_dwordx4 v[210:211], off
	v_lshl_add_u64 v[210:211], v[212:213], 0, s[2:3]
	s_add_i32 m0, s35, 0x2000
	s_nop 0
	global_load_lds_dwordx4 v[210:211], off
	s_barrier
	s_waitcnt lgkmcnt(0)
	v_mfma_f32_16x16x32_f16 v[126:129], v[178:181], v[142:145], v[126:129]
	v_mfma_f32_16x16x32_f16 v[122:125], v[186:189], v[142:145], v[122:125]
	v_mfma_f32_16x16x32_f16 v[110:113], v[178:181], v[150:153], v[110:113]
	v_mfma_f32_16x16x32_f16 v[106:109], v[186:189], v[150:153], v[106:109]
	v_mfma_f32_16x16x32_f16 v[94:97], v[178:181], v[158:161], v[94:97]
	v_mfma_f32_16x16x32_f16 v[90:93], v[186:189], v[158:161], v[90:93]
	v_mfma_f32_16x16x32_f16 v[78:81], v[178:181], v[170:173], v[78:81]
	v_mfma_f32_16x16x32_f16 v[74:77], v[186:189], v[170:173], v[74:77]
	v_mfma_f32_16x16x32_f16 v[126:129], v[182:185], v[146:149], v[126:129]
	v_mfma_f32_16x16x32_f16 v[122:125], v[190:193], v[146:149], v[122:125]
	v_mfma_f32_16x16x32_f16 v[110:113], v[182:185], v[154:157], v[110:113]
	v_mfma_f32_16x16x32_f16 v[106:109], v[190:193], v[154:157], v[106:109]
	v_mfma_f32_16x16x32_f16 v[94:97], v[182:185], v[166:169], v[94:97]
	v_mfma_f32_16x16x32_f16 v[90:93], v[190:193], v[166:169], v[90:93]
	v_mfma_f32_16x16x32_f16 v[78:81], v[182:185], v[174:177], v[78:81]
	v_mfma_f32_16x16x32_f16 v[74:77], v[190:193], v[174:177], v[74:77]
	s_mov_b32 m0, s71
	v_lshl_add_u64 v[210:211], v[214:215], 0, s[2:3]
	s_barrier
	ds_read_b128 v[142:145], v248 offset:49152
	ds_read_b128 v[146:149], v248 offset:50176
	ds_read_b128 v[150:153], v248 offset:51200
	ds_read_b128 v[154:157], v248 offset:52224
	ds_read_b128 v[158:161], v248 offset:53248
	ds_read_b128 v[166:169], v248 offset:54272
	ds_read_b128 v[170:173], v248 offset:55296
	ds_read_b128 v[174:177], v248 offset:56320
	global_load_lds_dwordx4 v[210:211], off
	v_lshl_add_u64 v[210:211], v[216:217], 0, s[2:3]
	s_mov_b32 m0, s82
	s_nop 0
	global_load_lds_dwordx4 v[210:211], off
	s_barrier
; #define LAS __attribute__((address_space(3)))
; #define PG8_STAGE(bufoff, gbase, voff) do { _Pragma("unroll") for (int _i = 0; _i < 2; ++_i) \
;     __builtin_amdgcn_global_load_lds((const unsigned*)((const char*)(gbase) + (voff)[_i]), (LAS unsigned*)(lds + (bufoff) + ldsw + _i * 8192), 16, 0, 0); } while (0)
; template <class Epi>
; DI void gemm_phase(int wv, LAS unsigned char* lds, const Gemm g, const StaticOrder& S, const Epi& E) {
;     ...
;       PG8_BAR; PG8_WAIT_L(0); PG8_MMA(1, 0, At, B0); PG8_BAR; PG8_SCHED;
;       PG8_STAGE(PG8_SB(1, 1), b3 + hstep, voffA);
;       PG8_WAIT_V(6); PG8_BAR; PG8_MMA(1, 1, At, B1); PG8_BAR;
;   DI void operator()(const f32x4 (&acc)[2][2][4][2], const pg8::Unit& u, int wr, int wc, int fr, int fq, LAS unsigned char* lds, int ui, int wid) const {
;     const int col0 = u.pn * 256 + wc * 32 + 8 * fq;
;     int fq_ = fq, fr_ = fr; asm volatile("" : "+v"(fq_), "+v"(fr_));
;     const LAS float* gl = (const LAS float*)(lds + 139264 + (ui & 1) * 3072) + wc * 32 + 8 * fq_;
;     const LAS float* sl = (const LAS float*)(lds + 131072 + wid * 1024);
;     float rmu[8], rrs[8];
; #pragma unroll
;     for (int i = 0; i < 8; ++i) { typedef float f32x2_ __attribute__((ext_vector_type(2))); const f32x2_ sv = *(const LAS f32x2_*)(sl + (i >> 2) * 128 + ((i & 3) * 16 + fr_) * 2);
;       const float mu = sv.x * (1.0f / 1024.0f), var = fmaxf(sv.y * (1.0f / 1024.0f) - mu * mu, 0.f); rmu[i] = mu; rrs[i] = rsqrtf(var + 1e-5f); }
; #pragma unroll
;     for (int ai = 0; ai < 2; ++ai) {
;       half8 tpv[4][2];
; #pragma unroll
;       for (int m = 0; m < 4; ++m)
; #pragma unroll
;         for (int bj = 0; bj < 2; ++bj) tpv[m][bj] = *(const half8*)(tb + (size_t)(u.pm * 256 + ai * 128 + wr * 64 + m * 16 + fr) * DM + col0 + bj * 128);
; #pragma unroll
;       for (int m = 0; m < 4; ++m) {
;         const int row = u.pm * 256 + ai * 128 + wr * 64 + m * 16 + fr; const float mu = rmu[ai * 4 + m], rstd = rrs[ai * 4 + m];
;         float rs = 0.f, rq = 0.f;
; #pragma unroll
;         for (int bj = 0; bj < 2; ++bj) {
;           u32x4 w;
; #pragma unroll
;           for (int n = 0; n < 2; ++n) {
;             f32x4 tp;
; #pragma unroll
;             for (int j = 0; j < 4; ++j) tp[j] = (float)tpv[m][bj][4 * n + j];
;             tp = (tp - mu) * rstd * (*(const LAS f32x4*)(gl + bj * 128 + 4 * n)) + *(const LAS f32x4*)(gl + 256 + bj * 128 + 4 * n);
	s_waitcnt lgkmcnt(0)
	v_mfma_f32_16x16x32_f16 v[70:73], v[58:61], v[142:145], v[70:73]
	v_mfma_f32_16x16x32_f16 v[62:65], v[130:133], v[142:145], v[62:65]
	v_mfma_f32_16x16x32_f16 v[46:49], v[58:61], v[150:153], v[46:49]
	v_mfma_f32_16x16x32_f16 v[42:45], v[130:133], v[150:153], v[42:45]
	v_mfma_f32_16x16x32_f16 v[28:31], v[58:61], v[158:161], v[28:31]
	v_mfma_f32_16x16x32_f16 v[24:27], v[130:133], v[158:161], v[24:27]
	v_mfma_f32_16x16x32_f16 v[12:15], v[58:61], v[170:173], v[12:15]
	v_mfma_f32_16x16x32_f16 v[8:11], v[130:133], v[170:173], v[8:11]
	v_mfma_f32_16x16x32_f16 v[70:73], v[66:69], v[146:149], v[70:73]
	v_mfma_f32_16x16x32_f16 v[62:65], v[138:141], v[146:149], v[62:65]
	v_mfma_f32_16x16x32_f16 v[46:49], v[66:69], v[154:157], v[46:49]
	v_mfma_f32_16x16x32_f16 v[42:45], v[138:141], v[154:157], v[42:45]
	v_mfma_f32_16x16x32_f16 v[28:31], v[66:69], v[166:169], v[28:31]
	v_mfma_f32_16x16x32_f16 v[24:27], v[138:141], v[166:169], v[24:27]
	v_mfma_f32_16x16x32_f16 v[12:15], v[66:69], v[174:177], v[12:15]
	v_mfma_f32_16x16x32_f16 v[8:11], v[138:141], v[174:177], v[8:11]
	s_barrier
	s_add_i32 s34, s34, s57
	v_lshl_add_u64 v[58:59], v[218:219], 0, s[2:3]
	s_mov_b32 m0, s34
	s_nop 0
	global_load_lds_dwordx4 v[58:59], off
	v_lshl_add_u64 v[58:59], v[220:221], 0, s[2:3]
	s_add_i32 m0, s34, 0x2000
	s_nop 0
	global_load_lds_dwordx4 v[58:59], off
	s_waitcnt vmcnt(6)
	s_barrier
	v_mfma_f32_16x16x32_f16 v[54:57], v[178:181], v[142:145], v[54:57]
	v_mfma_f32_16x16x32_f16 v[50:53], v[186:189], v[142:145], v[50:53]
	v_mfma_f32_16x16x32_f16 v[38:41], v[178:181], v[150:153], v[38:41]
	v_mfma_f32_16x16x32_f16 v[34:37], v[186:189], v[150:153], v[34:37]
	v_mfma_f32_16x16x32_f16 v[20:23], v[178:181], v[158:161], v[20:23]
	v_mfma_f32_16x16x32_f16 v[16:19], v[186:189], v[158:161], v[16:19]
	v_mfma_f32_16x16x32_f16 v[4:7], v[178:181], v[170:173], v[4:7]
	v_mfma_f32_16x16x32_f16 v[0:3], v[186:189], v[170:173], v[0:3]
	v_mfma_f32_16x16x32_f16 v[54:57], v[182:185], v[146:149], v[54:57]
	v_mfma_f32_16x16x32_f16 v[50:53], v[190:193], v[146:149], v[50:53]
	v_mfma_f32_16x16x32_f16 v[38:41], v[182:185], v[154:157], v[38:41]
	v_mfma_f32_16x16x32_f16 v[34:37], v[190:193], v[154:157], v[34:37]
	v_mfma_f32_16x16x32_f16 v[20:23], v[182:185], v[166:169], v[20:23]
	v_mfma_f32_16x16x32_f16 v[16:19], v[190:193], v[166:169], v[16:19]
	v_mfma_f32_16x16x32_f16 v[4:7], v[182:185], v[174:177], v[4:7]
	v_mfma_f32_16x16x32_f16 v[0:3], v[190:193], v[174:177], v[0:3]
	s_add_u32 s30, s30, 0x100
	s_addc_u32 s31, s31, 0
	s_add_u32 s95, s95, 0x100
	s_addc_u32 vcc_lo, vcc_lo, 0
	s_cmp_ge_u32 vcc_hi, s51
	s_mov_b32 s34, vcc_hi
	s_barrier
	s_cbranch_scc0 .LBB0_890
	v_mov_b32_e32 v58, v243
	v_mov_b32_e32 v59, v244
	s_mov_b32 s36, 0x800000
	v_lshlrev_b32_e32 v138, 5, v58
	v_lshl_add_u32 v58, v59, 3, s63
	ds_read2_b64 v[168:171], v58 offset1:16
	s_bitcmp1_b32 s94, 0
	v_lshl_add_u32 v212, s78, 8, v245
	s_cselect_b32 s30, 0xc00, 0
	v_or_b32_e32 v220, 32, v212
	s_waitcnt lgkmcnt(0)
	v_pk_mul_f32 v[192:193], v[168:169], s[44:45] op_sel_hi:[1,0]
	s_add_i32 s30, s86, s30
	v_fma_f32 v59, -v192, v192, v193
	v_max_f32_e32 v59, 0, v59
	v_add_f32_e32 v59, 0x3727c5ac, v59
	v_cmp_gt_f32_e32 vcc, s36, v59
	v_mul_f32_e32 v60, 0x4b800000, v59
	v_ashrrev_i32_e32 v221, 31, v220
	v_cndmask_b32_e32 v59, v59, v60, vcc
	v_rsq_f32_e32 v59, v59
	v_and_b32_e32 v139, 64, v240
	v_lshlrev_b64 v[222:223], 11, v[220:221]
	v_add_u32_e32 v221, s30, v138
	v_mul_f32_e32 v60, 0x45800000, v59
	v_xor_b32_e32 v138, 16, v240
	v_add_u32_e32 v139, 64, v139
	v_or_b32_e32 v214, 48, v212
	v_cndmask_b32_e32 v228, v59, v60, vcc
	v_cmp_lt_i32_e32 vcc, v138, v139
	v_lshl_or_b32 v210, s79, 8, v247
	v_ashrrev_i32_e32 v215, 31, v214
	v_cndmask_b32_e32 v138, v240, v138, vcc
	v_ashrrev_i32_e32 v211, 31, v210
	v_lshlrev_b64 v[218:219], 11, v[214:215]
	v_lshlrev_b32_e32 v215, 2, v138
	v_xor_b32_e32 v138, 32, v240
	v_ashrrev_i32_e32 v213, 31, v212
	v_cmp_lt_i32_e32 vcc, v138, v139
	v_lshlrev_b64 v[190:191], 1, v[210:211]
	v_lshlrev_b64 v[184:185], 11, v[212:213]
	v_cndmask_b32_e32 v138, v240, v138, vcc
	v_lshl_add_u64 v[216:217], s[76:77], 0, v[190:191]
	v_lshlrev_b32_e32 v213, 2, v138
	v_lshl_add_u64 v[138:139], v[216:217], 0, v[184:185]
	ds_read2_b64 v[130:133], v58 offset0:32 offset1:48
	ds_read2_b64 v[66:69], v58 offset0:64 offset1:80
	ds_read2_b64 v[58:61], v58 offset0:96 offset1:112
	global_load_dwordx4 v[180:183], v[138:139], off
	global_load_dwordx4 v[186:189], v[138:139], off offset:256
	v_or_b32_e32 v224, 16, v212
	v_ashrrev_i32_e32 v225, 31, v224
	v_lshlrev_b64 v[226:227], 11, v[224:225]
	v_lshl_add_u64 v[138:139], v[216:217], 0, v[226:227]
	global_load_dwordx4 v[176:179], v[138:139], off
	global_load_dwordx4 v[172:175], v[138:139], off offset:256
	v_lshl_add_u64 v[138:139], v[216:217], 0, v[222:223]
	global_load_dwordx4 v[166:169], v[138:139], off
	global_load_dwordx4 v[158:161], v[138:139], off offset:256
	v_lshl_add_u64 v[138:139], v[216:217], 0, v[218:219]
	global_load_dwordx4 v[142:145], v[138:139], off
	s_nop 0
	global_load_dwordx4 v[138:141], v[138:139], off offset:256
	s_waitcnt vmcnt(7)
	v_cvt_f32_f16_sdwa v149, v180 dst_sel:DWORD dst_unused:UNUSED_PAD src0_sel:WORD_1
	v_cvt_f32_f16_e32 v148, v180
	v_cvt_f32_f16_sdwa v147, v181 dst_sel:DWORD dst_unused:UNUSED_PAD src0_sel:WORD_1
	v_cvt_f32_f16_e32 v146, v181
	v_sub_f32_e32 v149, v149, v192
	v_sub_f32_e32 v148, v148, v192
	v_sub_f32_e32 v147, v147, v192
	v_sub_f32_e32 v146, v146, v192
	v_pk_mul_f32 v[180:181], v[228:229], v[148:149] op_sel_hi:[0,1]
	v_pk_mul_f32 v[230:231], v[228:229], v[146:147] op_sel_hi:[0,1]
	ds_read_b128 v[150:153], v221
	ds_read_b128 v[146:149], v221 offset:16
	ds_read_b128 v[154:157], v221 offset:1024
	s_waitcnt lgkmcnt(0)
; #define LAS __attribute__((address_space(3)))
; DI unsigned pkh2(float a, float b) { typedef _Float16 h2 __attribute__((ext_vector_type(2))); h2 v; v[0] = (_Float16)a; v[1] = (_Float16)b; return __builtin_bit_cast(unsigned, v); }
;   DI void operator()(const f32x4 (&acc)[2][2][4][2], const pg8::Unit& u, int wr, int wc, int fr, int fq, LAS unsigned char* lds, int ui, int wid) const {
;     ...
;         const int row = u.pm * 256 + ai * 128 + wr * 64 + m * 16 + fr; const float mu = rmu[ai * 4 + m], rstd = rrs[ai * 4 + m];
;         float rs = 0.f, rq = 0.f;
; #pragma unroll
;         for (int bj = 0; bj < 2; ++bj) {
;           u32x4 w;
; #pragma unroll
;           for (int n = 0; n < 2; ++n) {
;             f32x4 tp;
; #pragma unroll
;             for (int j = 0; j < 4; ++j) tp[j] = (float)tpv[m][bj][4 * n + j];
;             tp = (tp - mu) * rstd * (*(const LAS f32x4*)(gl + bj * 128 + 4 * n)) + *(const LAS f32x4*)(gl + 256 + bj * 128 + 4 * n);
;             const f32x4 tn = tp * ALPHA + acc[ai][bj][m][n] * scale;
;             w[2 * n] = pkh2(tn[0], tn[1]); w[2 * n + 1] = pkh2(tn[2], tn[3]);
;             rs += tn[0] + tn[1] + tn[2] + tn[3]; rq += tn[0] * tn[0] + tn[1] * tn[1] + tn[2] * tn[2] + tn[3] * tn[3];
;           }
;           *(u32x4*)(tb + (size_t)row * DM + col0 + bj * 128) = w;
;         }
;         rs += __shfl_xor(rs, 16); rs += __shfl_xor(rs, 32); rq += __shfl_xor(rq, 16); rq += __shfl_xor(rq, 32);
;         if (fq == 0) { atomicAdd(stats_new + 2 * row, rs); atomicAdd(stats_new + 2 * row + 1, rq); }
	v_pk_fma_f32 v[180:181], v[180:181], v[150:151], v[154:155]
	s_nop 0
	v_pk_mul_f32 v[180:181], v[180:181], s[52:53] op_sel_hi:[1,0]
	v_pk_fma_f32 v[230:231], v[230:231], v[152:153], v[156:157]
	v_pk_fma_f32 v[162:163], s[12:13], v[162:163], v[180:181]
	v_pk_mul_f32 v[230:231], v[230:231], s[52:53] op_sel_hi:[1,0]
	v_mul_f32_e32 v225, v163, v163
	v_pk_fma_f32 v[164:165], s[14:15], v[164:165], v[230:231]
	v_add_f32_e32 v193, v162, v163
	v_fmac_f32_e32 v225, v162, v162
	v_add_f32_e32 v193, v164, v193
	v_fmac_f32_e32 v225, v164, v164
	v_cvt_pk_f16_f32 v180, v162, v163
	v_cvt_pk_f16_f32 v181, v164, v165
	v_add_f32_e32 v193, v165, v193
	v_fmac_f32_e32 v225, v165, v165
	v_cvt_f32_f16_sdwa v165, v182 dst_sel:DWORD dst_unused:UNUSED_PAD src0_sel:WORD_1
	v_cvt_f32_f16_e32 v164, v182
	v_cvt_f32_f16_sdwa v163, v183 dst_sel:DWORD dst_unused:UNUSED_PAD src0_sel:WORD_1
	v_cvt_f32_f16_e32 v162, v183
	v_sub_f32_e32 v165, v165, v192
	v_sub_f32_e32 v164, v164, v192
	v_sub_f32_e32 v163, v163, v192
	v_sub_f32_e32 v162, v162, v192
	v_pk_mul_f32 v[182:183], v[228:229], v[164:165] op_sel_hi:[0,1]
	v_pk_mul_f32 v[230:231], v[228:229], v[162:163] op_sel_hi:[0,1]
	ds_read_b128 v[162:165], v221 offset:1040
	v_add_f32_e32 v193, 0, v193
	s_waitcnt lgkmcnt(0)
	v_pk_fma_f32 v[182:183], v[182:183], v[146:147], v[162:163]
	v_pk_fma_f32 v[230:231], v[230:231], v[148:149], v[164:165]
	v_pk_mul_f32 v[182:183], v[182:183], s[52:53] op_sel_hi:[1,0]
	v_pk_mul_f32 v[230:231], v[230:231], s[52:53] op_sel_hi:[1,0]
	v_pk_fma_f32 v[134:135], s[12:13], v[134:135], v[182:183]
	v_pk_fma_f32 v[136:137], s[14:15], v[136:137], v[230:231]
	v_cvt_pk_f16_f32 v182, v134, v135
	v_add_f32_e32 v230, v134, v135
	v_mul_f32_e32 v135, v135, v135
	v_fmac_f32_e32 v135, v134, v134
	v_fmac_f32_e32 v135, v136, v136
	v_add_f32_e32 v230, v136, v230
	v_fmac_f32_e32 v135, v137, v137
	v_add_f32_e32 v230, v137, v230
	v_add_f32_e32 v225, v225, v135
	v_lshl_add_u64 v[134:135], s[76:77], 0, v[184:185]
	v_cvt_pk_f16_f32 v183, v136, v137
	v_add_f32_e32 v193, v193, v230
	v_lshl_add_u64 v[230:231], v[134:135], 0, v[190:191]
	s_waitcnt vmcnt(6)
	v_cvt_f32_f16_sdwa v137, v186 dst_sel:DWORD dst_unused:UNUSED_PAD src0_sel:WORD_1
	v_cvt_f32_f16_e32 v136, v186
	v_cvt_f32_f16_sdwa v135, v187 dst_sel:DWORD dst_unused:UNUSED_PAD src0_sel:WORD_1
	v_cvt_f32_f16_e32 v134, v187
	global_store_dwordx4 v[230:231], v[180:183], off
	v_sub_f32_e32 v136, v136, v192
	v_sub_f32_e32 v135, v135, v192
	v_sub_f32_e32 v134, v134, v192
	v_sub_f32_e32 v137, v137, v192
	v_pk_mul_f32 v[190:191], v[228:229], v[136:137] op_sel_hi:[0,1]
	v_pk_mul_f32 v[250:251], v[228:229], v[134:135] op_sel_hi:[0,1]
	ds_read_b128 v[180:183], v221 offset:512
	ds_read_b128 v[134:137], v221 offset:528
	ds_read_b128 v[184:187], v221 offset:1536
	s_waitcnt lgkmcnt(0)
	v_pk_fma_f32 v[190:191], v[190:191], v[180:181], v[184:185]
	s_nop 0
	v_pk_mul_f32 v[190:191], v[190:191], s[52:53] op_sel_hi:[1,0]
	v_pk_fma_f32 v[250:251], v[250:251], v[182:183], v[186:187]
	v_pk_fma_f32 v[126:127], s[12:13], v[126:127], v[190:191]
	v_pk_mul_f32 v[250:251], v[250:251], s[52:53] op_sel_hi:[1,0]
	v_cvt_pk_f16_f32 v190, v126, v127
	v_add_f32_e32 v249, v126, v127
	v_mul_f32_e32 v127, v127, v127
	v_pk_fma_f32 v[128:129], s[14:15], v[128:129], v[250:251]
	v_fmac_f32_e32 v127, v126, v126
	v_fmac_f32_e32 v127, v128, v128
	v_add_f32_e32 v249, v128, v249
	v_fmac_f32_e32 v127, v129, v129
	v_cvt_pk_f16_f32 v191, v128, v129
	v_add_f32_e32 v249, v129, v249
	v_add_f32_e32 v225, v225, v127
	v_cvt_f32_f16_sdwa v129, v188 dst_sel:DWORD dst_unused:UNUSED_PAD src0_sel:WORD_1
	v_cvt_f32_f16_e32 v128, v188
	v_cvt_f32_f16_sdwa v127, v189 dst_sel:DWORD dst_unused:UNUSED_PAD src0_sel:WORD_1
	v_cvt_f32_f16_e32 v126, v189
	v_sub_f32_e32 v129, v129, v192
	v_sub_f32_e32 v128, v128, v192
	v_sub_f32_e32 v127, v127, v192
	v_sub_f32_e32 v126, v126, v192
	v_add_f32_e32 v249, v193, v249
	v_pk_mul_f32 v[188:189], v[228:229], v[128:129] op_sel_hi:[0,1]
	v_pk_mul_f32 v[192:193], v[228:229], v[126:127] op_sel_hi:[0,1]
	ds_read_b128 v[126:129], v221 offset:1552
	s_waitcnt lgkmcnt(0)
	v_pk_fma_f32 v[188:189], v[188:189], v[134:135], v[126:127]
	v_pk_fma_f32 v[192:193], v[192:193], v[136:137], v[128:129]
	v_pk_mul_f32 v[188:189], v[188:189], s[52:53] op_sel_hi:[1,0]
	v_pk_mul_f32 v[192:193], v[192:193], s[52:53] op_sel_hi:[1,0]
	v_pk_fma_f32 v[122:123], s[12:13], v[122:123], v[188:189]
	v_pk_fma_f32 v[124:125], s[14:15], v[124:125], v[192:193]
	v_cvt_pk_f16_f32 v192, v122, v123
	v_add_f32_e32 v188, v122, v123
	v_mul_f32_e32 v123, v123, v123
	v_fmac_f32_e32 v123, v122, v122
	v_add_f32_e32 v188, v124, v188
	v_fmac_f32_e32 v123, v124, v124
	v_add_f32_e32 v188, v125, v188
	v_fmac_f32_e32 v123, v125, v125
	v_cvt_pk_f16_f32 v193, v124, v125
	v_add_f32_e32 v188, v249, v188
	v_add_f32_e32 v124, v225, v123
	v_mov_b32_e32 v122, v188
	v_mov_b32_e32 v125, v124
	global_store_dwordx4 v[230:231], v[190:193], off offset:256
	s_nop 1
	v_permlane16_swap_b32_e32 v122, v188
	v_permlane16_swap_b32_e32 v125, v124
	v_add_f32_e32 v122, v188, v122
	s_waitcnt lgkmcnt(0)
	v_add_f32_e32 v124, v124, v125
	v_mov_b32_e32 v123, v122
	v_mov_b32_e32 v125, v124
	s_nop 1
	v_permlane32_swap_b32_e32 v123, v122
	v_permlane32_swap_b32_e32 v125, v124
	s_and_saveexec_b64 s[30:31], s[6:7]
	s_cbranch_execz .LBB0_893
	v_lshlrev_b32_e32 v188, 1, v212
	v_ashrrev_i32_e32 v189, 31, v188
	v_lshl_add_u64 v[188:189], v[188:189], 2, s[16:17]
	s_waitcnt lgkmcnt(1)
	v_add_f32_e32 v122, v122, v123
	s_waitcnt lgkmcnt(0)
	v_add_f32_e32 v123, v124, v125
	global_atomic_add_f32 v[188:189], v122, off
	global_atomic_add_f32 v[188:189], v123, off offset:4
